# hoist all 16 in-place residual loads of the W_o / down-GEMM-2 epilogues ahead of the stores and atomics (was load-wait-store serial per row slab)
# speedup vs baseline: 1.0250x; 1.0014x over previous
; __device__ __forceinline__ unsigned cvt_pk_bf16(float lo, float hi) { unsigned r; asm volatile("v_cvt_pk_bf16_f32 %0, %1, %2" : "=v"(r) : "v"(lo), "v"(hi)); return r; }
; template <class Epi> __device__ __forceinline__ void epi_all(const Epi& E, const f32x4 (&acc)[2][2][4][2], const Unit& u, int wr, int wc, int fr, int fq, const float (&rsq)[8]) {
;     const int row0 = u.pm * BM + wr * 64 + fr;
; #pragma unroll
;     for (int ai = 0; ai < 2; ++ai)
; #pragma unroll
;         for (int m = 0; m < 4; ++m) { const f32x4 v[2][2] = {{acc[ai][0][m][0], acc[ai][0][m][1]}, {acc[ai][1][m][0], acc[ai][1][m][1]}}; E.row(v, u, row0 + ai * HALF + m * 16, wc, fq, rsq[ai * 4 + m]); }
; }
;     __device__ __forceinline__ void row(const f32x4 (&v)[2][2], const Unit& u, int row, int wc, int fq, float) const {
;         const int col0 = u.pn * BM + wc * 32 + 8 * fq;
;         const float* rbase = (u.pm < MP / BM) ? resid_p : resid_s - (size_t)MP * DM;
;         const size_t off = (size_t)row * DM + col0; float ss = 0.f;
; #pragma unroll
;         for (int bj = 0; bj < 2; ++bj) {
;             f32x4 r0, r1;
;             if (rbf) { const u32x4 w = *(const u32x4*)(rbf + off + bj * HALF);
;                 r0 = (f32x4){__uint_as_float(w.x << 16), __uint_as_float(w.x & 0xffff0000u), __uint_as_float(w.y << 16), __uint_as_float(w.y & 0xffff0000u)};
;                 r1 = (f32x4){__uint_as_float(w.z << 16), __uint_as_float(w.z & 0xffff0000u), __uint_as_float(w.w << 16), __uint_as_float(w.w & 0xffff0000u)}; }
;             else { r0 = *(const f32x4*)(rbase + off + bj * HALF); r1 = *(const f32x4*)(rbase + off + bj * HALF + 4); }
;             const f32x4 v0 = r0 + v[bj][0] * alpha, v1 = r1 + v[bj][1] * alpha;
;             ss += (v0[0] * v0[0] + v0[1] * v0[1]) + (v0[2] * v0[2] + v0[3] * v0[3]) + (v1[0] * v1[0] + v1[1] * v1[1]) + (v1[2] * v1[2] + v1[3] * v1[3]);
;             u32x4 w; w.x = cvt_pk_bf16(v0[0], v0[1]); w.y = cvt_pk_bf16(v0[2], v0[3]); w.z = cvt_pk_bf16(v1[0], v1[1]); w.w = cvt_pk_bf16(v1[2], v1[3]);
;             *(u32x4*)(hb + off + bj * HALF) = w; }
;         ss += __shfl_xor(ss, 16); ss += __shfl_xor(ss, 32);
;         if (fq == 0) atomicAdd(rowss + row, ss);
.LBB0_1524:
	v_lshl_add_u32 v162, s66, 8, v136
	v_ashrrev_i32_e32 v163, 31, v162
	v_lshl_or_b32 v160, s64, 8, v137
	v_lshlrev_b64 v[164:165], 12, v[162:163]
	s_waitcnt lgkmcnt(0)
	v_ashrrev_i32_e32 v161, 31, v160
	v_lshl_add_u64 v[164:165], s[20:21], 0, v[164:165]
	v_lshl_add_u64 v[168:169], v[160:161], 1, v[164:165]
	global_load_dwordx4 v[188:191], v[168:169], off
	global_load_dwordx4 v[192:195], v[168:169], off offset:256
	s_mov_b64 s[98:99], 0x10000
	v_lshl_add_u64 v[248:249], v[168:169], 0, s[98:99]
	global_load_dwordx4 v[196:199], v[248:249], off
	global_load_dwordx4 v[200:203], v[248:249], off offset:256
	s_mov_b64 s[98:99], 0x20000
	v_lshl_add_u64 v[248:249], v[168:169], 0, s[98:99]
	global_load_dwordx4 v[204:207], v[248:249], off
	global_load_dwordx4 v[208:211], v[248:249], off offset:256
	s_mov_b64 s[98:99], 0x30000
	v_lshl_add_u64 v[248:249], v[168:169], 0, s[98:99]
	global_load_dwordx4 v[212:215], v[248:249], off
	global_load_dwordx4 v[216:219], v[248:249], off offset:256
	s_mov_b64 s[98:99], 0x80000
	v_lshl_add_u64 v[248:249], v[168:169], 0, s[98:99]
	global_load_dwordx4 v[220:223], v[248:249], off
	global_load_dwordx4 v[224:227], v[248:249], off offset:256
	s_mov_b64 s[98:99], 0x90000
	v_lshl_add_u64 v[248:249], v[168:169], 0, s[98:99]
	global_load_dwordx4 v[228:231], v[248:249], off
	global_load_dwordx4 v[232:235], v[248:249], off offset:256
	s_mov_b64 s[98:99], 0xa0000
	v_lshl_add_u64 v[248:249], v[168:169], 0, s[98:99]
	global_load_dwordx4 v[236:239], v[248:249], off
	global_load_dwordx4 v[240:243], v[248:249], off offset:256
	s_mov_b64 s[98:99], 0xb0000
	v_lshl_add_u64 v[248:249], v[168:169], 0, s[98:99]
	global_load_dwordx4 v[244:247], v[248:249], off
	global_load_dwordx4 v[252:255], v[248:249], off offset:256
	v_xor_b32_e32 v176, 32, v187
	s_waitcnt vmcnt(15)
	v_lshlrev_b32_e32 v170, 16, v188
	v_and_b32_e32 v171, 0xffff0000, v188
	v_lshlrev_b32_e32 v164, 16, v189
	v_and_b32_e32 v165, 0xffff0000, v189
	v_lshlrev_b32_e32 v172, 16, v190
	v_and_b32_e32 v173, 0xffff0000, v190
	v_lshlrev_b32_e32 v166, 16, v191
	v_and_b32_e32 v167, 0xffff0000, v191
	v_pk_add_f32 v[126:127], v[126:127], v[164:165]
	v_pk_add_f32 v[170:171], v[124:125], v[170:171]
	v_pk_add_f32 v[174:175], v[122:123], v[166:167]
	v_pk_add_f32 v[172:173], v[120:121], v[172:173]
	v_cvt_pk_bf16_f32 v122, v170, v171
	v_cvt_pk_bf16_f32 v123, v126, v127
	v_mul_f32_e32 v171, v171, v171
	v_cvt_pk_bf16_f32 v124, v172, v173
	v_cvt_pk_bf16_f32 v125, v174, v175
	v_mul_f32_e32 v127, v127, v127
	v_mul_f32_e32 v173, v173, v173
	v_fmac_f32_e32 v171, v170, v170
	v_fmac_f32_e32 v127, v126, v126
	v_mul_f32_e32 v175, v175, v175
	v_fmac_f32_e32 v173, v172, v172
	v_add_f32_e32 v126, v171, v127
	v_fmac_f32_e32 v175, v174, v174
	v_add_f32_e32 v126, v173, v126
	v_add_f32_e32 v172, v175, v126
	v_and_b32_e32 v121, 64, v187
	v_xor_b32_e32 v120, 16, v187
	v_add_u32_e32 v121, 64, v121
	v_cmp_lt_i32_e32 vcc, v120, v121
	global_store_dwordx4 v[168:169], v[122:125], off
	s_waitcnt vmcnt(15)
	v_lshlrev_b32_e32 v126, 16, v192
	v_and_b32_e32 v127, 0xffff0000, v192
	v_lshlrev_b32_e32 v164, 16, v193
	v_and_b32_e32 v165, 0xffff0000, v193
	v_lshlrev_b32_e32 v170, 16, v194
	v_and_b32_e32 v171, 0xffff0000, v194
	v_pk_add_f32 v[118:119], v[118:119], v[164:165]
	v_pk_add_f32 v[116:117], v[116:117], v[126:127]
	v_lshlrev_b32_e32 v166, 16, v195
	v_and_b32_e32 v167, 0xffff0000, v195
	v_pk_add_f32 v[164:165], v[112:113], v[170:171]
	v_mul_f32_e32 v112, v117, v117
	v_mul_f32_e32 v113, v119, v119
	v_pk_add_f32 v[126:127], v[114:115], v[166:167]
	v_mul_f32_e32 v114, v165, v165
	v_fmac_f32_e32 v112, v116, v116
	v_fmac_f32_e32 v113, v118, v118
	v_mul_f32_e32 v115, v127, v127
	v_fmac_f32_e32 v114, v164, v164
	v_add_f32_e32 v112, v112, v113
	v_fmac_f32_e32 v115, v126, v126
	v_add_f32_e32 v112, v114, v112
	v_cndmask_b32_e32 v120, v187, v120, vcc
	v_add_f32_e32 v112, v115, v112
	v_lshlrev_b32_e32 v120, 2, v120
	v_add_f32_e32 v112, v172, v112
	ds_bpermute_b32 v113, v120, v112
	v_cmp_lt_i32_e32 vcc, v176, v121
	v_cvt_pk_bf16_f32 v116, v116, v117
	v_cvt_pk_bf16_f32 v117, v118, v119
	v_cvt_pk_bf16_f32 v118, v164, v165
	s_waitcnt lgkmcnt(0)
	v_add_f32_e32 v112, v112, v113
	v_cvt_pk_bf16_f32 v119, v126, v127
	v_cndmask_b32_e32 v114, v187, v176, vcc
	v_lshlrev_b32_e32 v114, 2, v114
	ds_bpermute_b32 v113, v114, v112
	global_store_dwordx4 v[168:169], v[116:119], off offset:256
	s_and_saveexec_b64 s[64:65], s[6:7]
	s_cbranch_execz .LBB0_1526
	v_lshl_add_u64 v[116:117], v[162:163], 2, s[18:19]
	s_waitcnt lgkmcnt(0)
	v_add_f32_e32 v112, v112, v113
	global_atomic_add_f32 v[116:117], v112, off
; __device__ __forceinline__ unsigned cvt_pk_bf16(float lo, float hi) { unsigned r; asm volatile("v_cvt_pk_bf16_f32 %0, %1, %2" : "=v"(r) : "v"(lo), "v"(hi)); return r; }
;     __device__ __forceinline__ void row(const f32x4 (&v)[2][2], const Unit& u, int row, int wc, int fq, float) const {
;         const int col0 = u.pn * BM + wc * 32 + 8 * fq;
;         const float* rbase = (u.pm < MP / BM) ? resid_p : resid_s - (size_t)MP * DM;
;         const size_t off = (size_t)row * DM + col0; float ss = 0.f;
; #pragma unroll
;         for (int bj = 0; bj < 2; ++bj) {
;             f32x4 r0, r1;
;             if (rbf) { const u32x4 w = *(const u32x4*)(rbf + off + bj * HALF);
;                 r0 = (f32x4){__uint_as_float(w.x << 16), __uint_as_float(w.x & 0xffff0000u), __uint_as_float(w.y << 16), __uint_as_float(w.y & 0xffff0000u)};
;                 r1 = (f32x4){__uint_as_float(w.z << 16), __uint_as_float(w.z & 0xffff0000u), __uint_as_float(w.w << 16), __uint_as_float(w.w & 0xffff0000u)}; }
;             else { r0 = *(const f32x4*)(rbase + off + bj * HALF); r1 = *(const f32x4*)(rbase + off + bj * HALF + 4); }
;             const f32x4 v0 = r0 + v[bj][0] * alpha, v1 = r1 + v[bj][1] * alpha;
;             ss += (v0[0] * v0[0] + v0[1] * v0[1]) + (v0[2] * v0[2] + v0[3] * v0[3]) + (v1[0] * v1[0] + v1[1] * v1[1]) + (v1[2] * v1[2] + v1[3] * v1[3]);
;             u32x4 w; w.x = cvt_pk_bf16(v0[0], v0[1]); w.y = cvt_pk_bf16(v0[2], v0[3]); w.z = cvt_pk_bf16(v1[0], v1[1]); w.w = cvt_pk_bf16(v1[2], v1[3]);
;             *(u32x4*)(hb + off + bj * HALF) = w; }
;         ss += __shfl_xor(ss, 16); ss += __shfl_xor(ss, 32);
;         if (fq == 0) atomicAdd(rowss + row, ss);
.LBB0_1526:
	s_or_b64 exec, exec, s[64:65]
	v_or_b32_e32 v112, 16, v162
	s_waitcnt lgkmcnt(0)
	v_ashrrev_i32_e32 v113, 31, v112
	v_lshlrev_b64 v[116:117], 12, v[112:113]
	v_lshl_add_u64 v[116:117], s[20:21], 0, v[116:117]
	v_lshl_add_u64 v[122:123], v[160:161], 1, v[116:117]
	s_waitcnt vmcnt(15)
	v_lshlrev_b32_e32 v124, 16, v196
	v_and_b32_e32 v125, 0xffff0000, v196
	v_lshlrev_b32_e32 v116, 16, v197
	v_and_b32_e32 v117, 0xffff0000, v197
	v_lshlrev_b32_e32 v126, 16, v198
	v_and_b32_e32 v127, 0xffff0000, v198
	v_lshlrev_b32_e32 v118, 16, v199
	v_and_b32_e32 v119, 0xffff0000, v199
	v_pk_add_f32 v[116:117], v[110:111], v[116:117]
	v_pk_add_f32 v[124:125], v[108:109], v[124:125]
	v_pk_add_f32 v[118:119], v[106:107], v[118:119]
	v_pk_add_f32 v[126:127], v[104:105], v[126:127]
	v_cvt_pk_bf16_f32 v104, v124, v125
	v_cvt_pk_bf16_f32 v105, v116, v117
	v_mul_f32_e32 v115, v125, v125
	v_cvt_pk_bf16_f32 v106, v126, v127
	v_cvt_pk_bf16_f32 v107, v118, v119
	v_mul_f32_e32 v117, v117, v117
	v_mul_f32_e32 v121, v127, v127
	v_fmac_f32_e32 v115, v124, v124
	v_fmac_f32_e32 v117, v116, v116
	v_mul_f32_e32 v119, v119, v119
	v_fmac_f32_e32 v121, v126, v126
	v_add_f32_e32 v115, v115, v117
	v_fmac_f32_e32 v119, v118, v118
	v_add_f32_e32 v115, v121, v115
	v_add_f32_e32 v115, v119, v115
	global_store_dwordx4 v[122:123], v[104:107], off
	s_waitcnt vmcnt(15)
	v_lshlrev_b32_e32 v116, 16, v200
	v_and_b32_e32 v117, 0xffff0000, v200
	v_lshlrev_b32_e32 v108, 16, v201
	v_and_b32_e32 v109, 0xffff0000, v201
	v_lshlrev_b32_e32 v118, 16, v202
	v_and_b32_e32 v119, 0xffff0000, v202
	v_lshlrev_b32_e32 v110, 16, v203
	v_and_b32_e32 v111, 0xffff0000, v203
	v_pk_add_f32 v[102:103], v[102:103], v[108:109]
	v_pk_add_f32 v[100:101], v[100:101], v[116:117]
	v_pk_add_f32 v[108:109], v[98:99], v[110:111]
	v_pk_add_f32 v[110:111], v[96:97], v[118:119]
	v_mul_f32_e32 v96, v101, v101
	v_mul_f32_e32 v97, v103, v103
	v_mul_f32_e32 v98, v111, v111
	v_fmac_f32_e32 v96, v100, v100
	v_fmac_f32_e32 v97, v102, v102
	v_mul_f32_e32 v99, v109, v109
	v_fmac_f32_e32 v98, v110, v110
	v_add_f32_e32 v96, v96, v97
	v_add_f32_e32 v96, v98, v96
	v_fmac_f32_e32 v99, v108, v108
	v_add_f32_e32 v96, v99, v96
	v_add_f32_e32 v96, v115, v96
	ds_bpermute_b32 v97, v120, v96
	v_cvt_pk_bf16_f32 v98, v100, v101
	v_cvt_pk_bf16_f32 v99, v102, v103
	v_cvt_pk_bf16_f32 v100, v110, v111
	v_cvt_pk_bf16_f32 v101, v108, v109
	s_waitcnt lgkmcnt(0)
	v_add_f32_e32 v96, v96, v97
	ds_bpermute_b32 v97, v114, v96
	global_store_dwordx4 v[122:123], v[98:101], off offset:256
	s_and_saveexec_b64 s[64:65], s[6:7]
	s_cbranch_execz .LBB0_1528
	v_lshl_add_u64 v[98:99], v[112:113], 2, s[18:19]
	s_waitcnt lgkmcnt(0)
	v_add_f32_e32 v96, v96, v97
	global_atomic_add_f32 v[98:99], v96, off
.LBB0_1528:
	s_or_b64 exec, exec, s[64:65]
	v_or_b32_e32 v96, 32, v162
	s_waitcnt lgkmcnt(0)
	v_ashrrev_i32_e32 v97, 31, v96
	v_lshlrev_b64 v[98:99], 12, v[96:97]
	v_lshl_add_u64 v[98:99], s[20:21], 0, v[98:99]
	v_lshl_add_u64 v[102:103], v[160:161], 1, v[98:99]
	s_waitcnt vmcnt(15)
	v_lshlrev_b32_e32 v104, 16, v204
	v_and_b32_e32 v105, 0xffff0000, v204
	v_lshlrev_b32_e32 v98, 16, v205
	v_and_b32_e32 v99, 0xffff0000, v205
	v_lshlrev_b32_e32 v106, 16, v206
	v_and_b32_e32 v107, 0xffff0000, v206
	v_lshlrev_b32_e32 v100, 16, v207
	v_and_b32_e32 v101, 0xffff0000, v207
	v_pk_add_f32 v[98:99], v[94:95], v[98:99]
	v_pk_add_f32 v[104:105], v[92:93], v[104:105]
	v_pk_add_f32 v[100:101], v[90:91], v[100:101]
	v_pk_add_f32 v[106:107], v[88:89], v[106:107]
	v_cvt_pk_bf16_f32 v88, v104, v105
	v_cvt_pk_bf16_f32 v89, v98, v99
	v_mul_f32_e32 v105, v105, v105
	v_cvt_pk_bf16_f32 v90, v106, v107
	v_cvt_pk_bf16_f32 v91, v100, v101
	v_mul_f32_e32 v99, v99, v99
	v_mul_f32_e32 v107, v107, v107
	v_fmac_f32_e32 v105, v104, v104
	v_fmac_f32_e32 v99, v98, v98
	v_mul_f32_e32 v101, v101, v101
	v_fmac_f32_e32 v107, v106, v106
	v_add_f32_e32 v98, v105, v99
	v_fmac_f32_e32 v101, v100, v100
	v_add_f32_e32 v98, v107, v98
	v_add_f32_e32 v104, v101, v98
	global_store_dwordx4 v[102:103], v[88:91], off
	s_waitcnt vmcnt(15)
	v_lshlrev_b32_e32 v98, 16, v208
	v_and_b32_e32 v99, 0xffff0000, v208
	v_lshlrev_b32_e32 v92, 16, v209
	v_and_b32_e32 v93, 0xffff0000, v209
	v_lshlrev_b32_e32 v100, 16, v210
	v_and_b32_e32 v101, 0xffff0000, v210
	v_lshlrev_b32_e32 v94, 16, v211
	v_and_b32_e32 v95, 0xffff0000, v211
	v_pk_add_f32 v[86:87], v[86:87], v[92:93]
	v_pk_add_f32 v[84:85], v[84:85], v[98:99]
	v_pk_add_f32 v[92:93], v[82:83], v[94:95]
	v_pk_add_f32 v[94:95], v[80:81], v[100:101]
	v_mul_f32_e32 v80, v85, v85
	v_mul_f32_e32 v81, v87, v87
	v_mul_f32_e32 v82, v95, v95
	v_fmac_f32_e32 v80, v84, v84
	v_fmac_f32_e32 v81, v86, v86
	v_mul_f32_e32 v83, v93, v93
	v_fmac_f32_e32 v82, v94, v94
	v_add_f32_e32 v80, v80, v81
	v_add_f32_e32 v80, v82, v80
	v_fmac_f32_e32 v83, v92, v92
	v_add_f32_e32 v80, v83, v80
	v_add_f32_e32 v80, v104, v80
	ds_bpermute_b32 v81, v120, v80
	v_cvt_pk_bf16_f32 v82, v84, v85
	v_cvt_pk_bf16_f32 v83, v86, v87
	v_cvt_pk_bf16_f32 v84, v94, v95
	v_cvt_pk_bf16_f32 v85, v92, v93
	s_waitcnt lgkmcnt(0)
	v_add_f32_e32 v80, v80, v81
	ds_bpermute_b32 v81, v114, v80
	global_store_dwordx4 v[102:103], v[82:85], off offset:256
	s_and_saveexec_b64 s[64:65], s[6:7]
	s_cbranch_execz .LBB0_1530
	v_lshl_add_u64 v[82:83], v[96:97], 2, s[18:19]
	s_waitcnt lgkmcnt(0)
	v_add_f32_e32 v80, v80, v81
	global_atomic_add_f32 v[82:83], v80, off
; __device__ __forceinline__ unsigned cvt_pk_bf16(float lo, float hi) { unsigned r; asm volatile("v_cvt_pk_bf16_f32 %0, %1, %2" : "=v"(r) : "v"(lo), "v"(hi)); return r; }
;     __device__ __forceinline__ void row(const f32x4 (&v)[2][2], const Unit& u, int row, int wc, int fq, float) const {
;         const int col0 = u.pn * BM + wc * 32 + 8 * fq;
;         const float* rbase = (u.pm < MP / BM) ? resid_p : resid_s - (size_t)MP * DM;
;         const size_t off = (size_t)row * DM + col0; float ss = 0.f;
; #pragma unroll
;         for (int bj = 0; bj < 2; ++bj) {
;             f32x4 r0, r1;
;             if (rbf) { const u32x4 w = *(const u32x4*)(rbf + off + bj * HALF);
;                 r0 = (f32x4){__uint_as_float(w.x << 16), __uint_as_float(w.x & 0xffff0000u), __uint_as_float(w.y << 16), __uint_as_float(w.y & 0xffff0000u)};
;                 r1 = (f32x4){__uint_as_float(w.z << 16), __uint_as_float(w.z & 0xffff0000u), __uint_as_float(w.w << 16), __uint_as_float(w.w & 0xffff0000u)}; }
;             else { r0 = *(const f32x4*)(rbase + off + bj * HALF); r1 = *(const f32x4*)(rbase + off + bj * HALF + 4); }
;             const f32x4 v0 = r0 + v[bj][0] * alpha, v1 = r1 + v[bj][1] * alpha;
;             ss += (v0[0] * v0[0] + v0[1] * v0[1]) + (v0[2] * v0[2] + v0[3] * v0[3]) + (v1[0] * v1[0] + v1[1] * v1[1]) + (v1[2] * v1[2] + v1[3] * v1[3]);
;             u32x4 w; w.x = cvt_pk_bf16(v0[0], v0[1]); w.y = cvt_pk_bf16(v0[2], v0[3]); w.z = cvt_pk_bf16(v1[0], v1[1]); w.w = cvt_pk_bf16(v1[2], v1[3]);
;             *(u32x4*)(hb + off + bj * HALF) = w; }
;         ss += __shfl_xor(ss, 16); ss += __shfl_xor(ss, 32);
;         if (fq == 0) atomicAdd(rowss + row, ss);
.LBB0_1530:
	s_or_b64 exec, exec, s[64:65]
	v_or_b32_e32 v80, 48, v162
	s_waitcnt lgkmcnt(0)
	v_ashrrev_i32_e32 v81, 31, v80
	v_lshlrev_b64 v[82:83], 12, v[80:81]
	v_lshl_add_u64 v[82:83], s[20:21], 0, v[82:83]
	v_lshl_add_u64 v[86:87], v[160:161], 1, v[82:83]
	s_waitcnt vmcnt(15)
	v_lshlrev_b32_e32 v88, 16, v212
	v_and_b32_e32 v89, 0xffff0000, v212
	v_lshlrev_b32_e32 v82, 16, v213
	v_and_b32_e32 v83, 0xffff0000, v213
	v_lshlrev_b32_e32 v90, 16, v214
	v_and_b32_e32 v91, 0xffff0000, v214
	v_lshlrev_b32_e32 v84, 16, v215
	v_and_b32_e32 v85, 0xffff0000, v215
	v_pk_add_f32 v[82:83], v[78:79], v[82:83]
	v_pk_add_f32 v[88:89], v[76:77], v[88:89]
	v_pk_add_f32 v[84:85], v[74:75], v[84:85]
	v_pk_add_f32 v[90:91], v[72:73], v[90:91]
	v_cvt_pk_bf16_f32 v72, v88, v89
	v_cvt_pk_bf16_f32 v73, v82, v83
	v_mul_f32_e32 v89, v89, v89
	v_cvt_pk_bf16_f32 v74, v90, v91
	v_cvt_pk_bf16_f32 v75, v84, v85
	v_mul_f32_e32 v83, v83, v83
	v_mul_f32_e32 v91, v91, v91
	v_fmac_f32_e32 v89, v88, v88
	v_fmac_f32_e32 v83, v82, v82
	v_mul_f32_e32 v85, v85, v85
	v_fmac_f32_e32 v91, v90, v90
	v_add_f32_e32 v82, v89, v83
	v_fmac_f32_e32 v85, v84, v84
	v_add_f32_e32 v82, v91, v82
	v_add_f32_e32 v88, v85, v82
	global_store_dwordx4 v[86:87], v[72:75], off
	s_waitcnt vmcnt(15)
	v_lshlrev_b32_e32 v82, 16, v216
	v_and_b32_e32 v83, 0xffff0000, v216
	v_lshlrev_b32_e32 v76, 16, v217
	v_and_b32_e32 v77, 0xffff0000, v217
	v_lshlrev_b32_e32 v84, 16, v218
	v_and_b32_e32 v85, 0xffff0000, v218
	v_lshlrev_b32_e32 v78, 16, v219
	v_and_b32_e32 v79, 0xffff0000, v219
	v_pk_add_f32 v[70:71], v[70:71], v[76:77]
	v_pk_add_f32 v[68:69], v[68:69], v[82:83]
	v_pk_add_f32 v[76:77], v[66:67], v[78:79]
	v_pk_add_f32 v[78:79], v[64:65], v[84:85]
	v_mul_f32_e32 v64, v69, v69
	v_mul_f32_e32 v65, v71, v71
	v_mul_f32_e32 v66, v79, v79
	v_fmac_f32_e32 v64, v68, v68
	v_fmac_f32_e32 v65, v70, v70
	v_mul_f32_e32 v67, v77, v77
	v_fmac_f32_e32 v66, v78, v78
	v_add_f32_e32 v64, v64, v65
	v_add_f32_e32 v64, v66, v64
	v_fmac_f32_e32 v67, v76, v76
	v_add_f32_e32 v64, v67, v64
	v_add_f32_e32 v64, v88, v64
	ds_bpermute_b32 v65, v120, v64
	v_cvt_pk_bf16_f32 v66, v68, v69
	v_cvt_pk_bf16_f32 v67, v70, v71
	v_cvt_pk_bf16_f32 v68, v78, v79
	v_cvt_pk_bf16_f32 v69, v76, v77
	s_waitcnt lgkmcnt(0)
	v_add_f32_e32 v64, v64, v65
	ds_bpermute_b32 v65, v114, v64
	global_store_dwordx4 v[86:87], v[66:69], off offset:256
	s_and_saveexec_b64 s[64:65], s[6:7]
	s_cbranch_execz .LBB0_1532
	v_lshl_add_u64 v[66:67], v[80:81], 2, s[18:19]
	s_waitcnt lgkmcnt(0)
	v_add_f32_e32 v64, v64, v65
	global_atomic_add_f32 v[66:67], v64, off
.LBB0_1532:
	s_or_b64 exec, exec, s[64:65]
	v_add_u32_e32 v64, 0x80, v162
	s_waitcnt lgkmcnt(0)
	v_ashrrev_i32_e32 v65, 31, v64
	v_lshlrev_b64 v[66:67], 12, v[64:65]
	v_lshl_add_u64 v[66:67], s[20:21], 0, v[66:67]
	v_lshl_add_u64 v[70:71], v[160:161], 1, v[66:67]
	s_waitcnt vmcnt(15)
	v_lshlrev_b32_e32 v72, 16, v220
	v_and_b32_e32 v73, 0xffff0000, v220
	v_lshlrev_b32_e32 v66, 16, v221
	v_and_b32_e32 v67, 0xffff0000, v221
	v_lshlrev_b32_e32 v74, 16, v222
	v_and_b32_e32 v75, 0xffff0000, v222
	v_lshlrev_b32_e32 v68, 16, v223
	v_and_b32_e32 v69, 0xffff0000, v223
	v_pk_add_f32 v[66:67], v[62:63], v[66:67]
	v_pk_add_f32 v[72:73], v[60:61], v[72:73]
	v_pk_add_f32 v[68:69], v[58:59], v[68:69]
	v_pk_add_f32 v[74:75], v[56:57], v[74:75]
	v_cvt_pk_bf16_f32 v56, v72, v73
	v_cvt_pk_bf16_f32 v57, v66, v67
	v_mul_f32_e32 v73, v73, v73
	v_cvt_pk_bf16_f32 v58, v74, v75
	v_cvt_pk_bf16_f32 v59, v68, v69
	v_mul_f32_e32 v67, v67, v67
	v_mul_f32_e32 v75, v75, v75
	v_fmac_f32_e32 v73, v72, v72
	v_fmac_f32_e32 v67, v66, v66
	v_mul_f32_e32 v69, v69, v69
	v_fmac_f32_e32 v75, v74, v74
	v_add_f32_e32 v66, v73, v67
	v_fmac_f32_e32 v69, v68, v68
	v_add_f32_e32 v66, v75, v66
	v_add_f32_e32 v72, v69, v66
	global_store_dwordx4 v[70:71], v[56:59], off
	s_waitcnt vmcnt(15)
	v_lshlrev_b32_e32 v66, 16, v224
	v_and_b32_e32 v67, 0xffff0000, v224
	v_lshlrev_b32_e32 v60, 16, v225
	v_and_b32_e32 v61, 0xffff0000, v225
	v_lshlrev_b32_e32 v68, 16, v226
	v_and_b32_e32 v69, 0xffff0000, v226
	v_lshlrev_b32_e32 v62, 16, v227
	v_and_b32_e32 v63, 0xffff0000, v227
	v_pk_add_f32 v[54:55], v[54:55], v[60:61]
	v_pk_add_f32 v[52:53], v[52:53], v[66:67]
	v_pk_add_f32 v[60:61], v[50:51], v[62:63]
	v_pk_add_f32 v[62:63], v[48:49], v[68:69]
	v_mul_f32_e32 v48, v53, v53
	v_mul_f32_e32 v49, v55, v55
	v_mul_f32_e32 v50, v63, v63
	v_fmac_f32_e32 v48, v52, v52
	v_fmac_f32_e32 v49, v54, v54
	v_mul_f32_e32 v51, v61, v61
	v_fmac_f32_e32 v50, v62, v62
	v_add_f32_e32 v48, v48, v49
	v_add_f32_e32 v48, v50, v48
	v_fmac_f32_e32 v51, v60, v60
	v_add_f32_e32 v48, v51, v48
	v_add_f32_e32 v48, v72, v48
	ds_bpermute_b32 v49, v120, v48
	v_cvt_pk_bf16_f32 v50, v52, v53
	v_cvt_pk_bf16_f32 v51, v54, v55
	v_cvt_pk_bf16_f32 v52, v62, v63
	v_cvt_pk_bf16_f32 v53, v60, v61
	s_waitcnt lgkmcnt(0)
	v_add_f32_e32 v48, v48, v49
	ds_bpermute_b32 v49, v114, v48
	global_store_dwordx4 v[70:71], v[50:53], off offset:256
	s_and_saveexec_b64 s[64:65], s[6:7]
	s_cbranch_execz .LBB0_1534
	v_lshl_add_u64 v[50:51], v[64:65], 2, s[18:19]
	s_waitcnt lgkmcnt(0)
	v_add_f32_e32 v48, v48, v49
	global_atomic_add_f32 v[50:51], v48, off
; __device__ __forceinline__ unsigned cvt_pk_bf16(float lo, float hi) { unsigned r; asm volatile("v_cvt_pk_bf16_f32 %0, %1, %2" : "=v"(r) : "v"(lo), "v"(hi)); return r; }
;     __device__ __forceinline__ void row(const f32x4 (&v)[2][2], const Unit& u, int row, int wc, int fq, float) const {
;         const int col0 = u.pn * BM + wc * 32 + 8 * fq;
;         const float* rbase = (u.pm < MP / BM) ? resid_p : resid_s - (size_t)MP * DM;
;         const size_t off = (size_t)row * DM + col0; float ss = 0.f;
; #pragma unroll
;         for (int bj = 0; bj < 2; ++bj) {
;             f32x4 r0, r1;
;             if (rbf) { const u32x4 w = *(const u32x4*)(rbf + off + bj * HALF);
;                 r0 = (f32x4){__uint_as_float(w.x << 16), __uint_as_float(w.x & 0xffff0000u), __uint_as_float(w.y << 16), __uint_as_float(w.y & 0xffff0000u)};
;                 r1 = (f32x4){__uint_as_float(w.z << 16), __uint_as_float(w.z & 0xffff0000u), __uint_as_float(w.w << 16), __uint_as_float(w.w & 0xffff0000u)}; }
;             else { r0 = *(const f32x4*)(rbase + off + bj * HALF); r1 = *(const f32x4*)(rbase + off + bj * HALF + 4); }
;             const f32x4 v0 = r0 + v[bj][0] * alpha, v1 = r1 + v[bj][1] * alpha;
;             ss += (v0[0] * v0[0] + v0[1] * v0[1]) + (v0[2] * v0[2] + v0[3] * v0[3]) + (v1[0] * v1[0] + v1[1] * v1[1]) + (v1[2] * v1[2] + v1[3] * v1[3]);
;             u32x4 w; w.x = cvt_pk_bf16(v0[0], v0[1]); w.y = cvt_pk_bf16(v0[2], v0[3]); w.z = cvt_pk_bf16(v1[0], v1[1]); w.w = cvt_pk_bf16(v1[2], v1[3]);
;             *(u32x4*)(hb + off + bj * HALF) = w; }
;         ss += __shfl_xor(ss, 16); ss += __shfl_xor(ss, 32);
;         if (fq == 0) atomicAdd(rowss + row, ss);
.LBB0_1534:
	s_or_b64 exec, exec, s[64:65]
	v_add_u32_e32 v48, 0x90, v162
	s_waitcnt lgkmcnt(0)
	v_ashrrev_i32_e32 v49, 31, v48
	v_lshlrev_b64 v[50:51], 12, v[48:49]
	v_lshl_add_u64 v[50:51], s[20:21], 0, v[50:51]
	v_lshl_add_u64 v[54:55], v[160:161], 1, v[50:51]
	s_waitcnt vmcnt(15)
	v_lshlrev_b32_e32 v56, 16, v228
	v_and_b32_e32 v57, 0xffff0000, v228
	v_lshlrev_b32_e32 v50, 16, v229
	v_and_b32_e32 v51, 0xffff0000, v229
	v_lshlrev_b32_e32 v58, 16, v230
	v_and_b32_e32 v59, 0xffff0000, v230
	v_lshlrev_b32_e32 v52, 16, v231
	v_and_b32_e32 v53, 0xffff0000, v231
	v_pk_add_f32 v[50:51], v[46:47], v[50:51]
	v_pk_add_f32 v[56:57], v[44:45], v[56:57]
	v_pk_add_f32 v[52:53], v[42:43], v[52:53]
	v_pk_add_f32 v[58:59], v[40:41], v[58:59]
	v_cvt_pk_bf16_f32 v40, v56, v57
	v_cvt_pk_bf16_f32 v41, v50, v51
	v_mul_f32_e32 v57, v57, v57
	v_cvt_pk_bf16_f32 v42, v58, v59
	v_cvt_pk_bf16_f32 v43, v52, v53
	v_mul_f32_e32 v51, v51, v51
	v_mul_f32_e32 v59, v59, v59
	v_fmac_f32_e32 v57, v56, v56
	v_fmac_f32_e32 v51, v50, v50
	v_mul_f32_e32 v53, v53, v53
	v_fmac_f32_e32 v59, v58, v58
	v_add_f32_e32 v50, v57, v51
	v_fmac_f32_e32 v53, v52, v52
	v_add_f32_e32 v50, v59, v50
	v_add_f32_e32 v56, v53, v50
	global_store_dwordx4 v[54:55], v[40:43], off
	s_waitcnt vmcnt(15)
	v_lshlrev_b32_e32 v50, 16, v232
	v_and_b32_e32 v51, 0xffff0000, v232
	v_lshlrev_b32_e32 v44, 16, v233
	v_and_b32_e32 v45, 0xffff0000, v233
	v_lshlrev_b32_e32 v52, 16, v234
	v_and_b32_e32 v53, 0xffff0000, v234
	v_lshlrev_b32_e32 v46, 16, v235
	v_and_b32_e32 v47, 0xffff0000, v235
	v_pk_add_f32 v[38:39], v[38:39], v[44:45]
	v_pk_add_f32 v[36:37], v[36:37], v[50:51]
	v_pk_add_f32 v[44:45], v[34:35], v[46:47]
	v_pk_add_f32 v[46:47], v[32:33], v[52:53]
	v_mul_f32_e32 v32, v37, v37
	v_mul_f32_e32 v33, v39, v39
	v_mul_f32_e32 v34, v47, v47
	v_fmac_f32_e32 v32, v36, v36
	v_fmac_f32_e32 v33, v38, v38
	v_mul_f32_e32 v35, v45, v45
	v_fmac_f32_e32 v34, v46, v46
	v_add_f32_e32 v32, v32, v33
	v_add_f32_e32 v32, v34, v32
	v_fmac_f32_e32 v35, v44, v44
	v_add_f32_e32 v32, v35, v32
	v_add_f32_e32 v32, v56, v32
	ds_bpermute_b32 v33, v120, v32
	v_cvt_pk_bf16_f32 v34, v36, v37
	v_cvt_pk_bf16_f32 v35, v38, v39
	v_cvt_pk_bf16_f32 v36, v46, v47
	v_cvt_pk_bf16_f32 v37, v44, v45
	s_waitcnt lgkmcnt(0)
	v_add_f32_e32 v32, v32, v33
	ds_bpermute_b32 v33, v114, v32
	global_store_dwordx4 v[54:55], v[34:37], off offset:256
	s_and_saveexec_b64 s[64:65], s[6:7]
	s_cbranch_execz .LBB0_1536
	v_lshl_add_u64 v[34:35], v[48:49], 2, s[18:19]
	s_waitcnt lgkmcnt(0)
	v_add_f32_e32 v32, v32, v33
	global_atomic_add_f32 v[34:35], v32, off
; __device__ __forceinline__ unsigned cvt_pk_bf16(float lo, float hi) { unsigned r; asm volatile("v_cvt_pk_bf16_f32 %0, %1, %2" : "=v"(r) : "v"(lo), "v"(hi)); return r; }
;     __device__ __forceinline__ void row(const f32x4 (&v)[2][2], const Unit& u, int row, int wc, int fq, float) const {
;         const int col0 = u.pn * BM + wc * 32 + 8 * fq;
;         const float* rbase = (u.pm < MP / BM) ? resid_p : resid_s - (size_t)MP * DM;
;         const size_t off = (size_t)row * DM + col0; float ss = 0.f;
; #pragma unroll
;         for (int bj = 0; bj < 2; ++bj) {
;             f32x4 r0, r1;
;             if (rbf) { const u32x4 w = *(const u32x4*)(rbf + off + bj * HALF);
;                 r0 = (f32x4){__uint_as_float(w.x << 16), __uint_as_float(w.x & 0xffff0000u), __uint_as_float(w.y << 16), __uint_as_float(w.y & 0xffff0000u)};
;                 r1 = (f32x4){__uint_as_float(w.z << 16), __uint_as_float(w.z & 0xffff0000u), __uint_as_float(w.w << 16), __uint_as_float(w.w & 0xffff0000u)}; }
;             else { r0 = *(const f32x4*)(rbase + off + bj * HALF); r1 = *(const f32x4*)(rbase + off + bj * HALF + 4); }
;             const f32x4 v0 = r0 + v[bj][0] * alpha, v1 = r1 + v[bj][1] * alpha;
;             ss += (v0[0] * v0[0] + v0[1] * v0[1]) + (v0[2] * v0[2] + v0[3] * v0[3]) + (v1[0] * v1[0] + v1[1] * v1[1]) + (v1[2] * v1[2] + v1[3] * v1[3]);
;             u32x4 w; w.x = cvt_pk_bf16(v0[0], v0[1]); w.y = cvt_pk_bf16(v0[2], v0[3]); w.z = cvt_pk_bf16(v1[0], v1[1]); w.w = cvt_pk_bf16(v1[2], v1[3]);
;             *(u32x4*)(hb + off + bj * HALF) = w; }
;         ss += __shfl_xor(ss, 16); ss += __shfl_xor(ss, 32);
;         if (fq == 0) atomicAdd(rowss + row, ss);
.LBB0_1536:
	s_or_b64 exec, exec, s[64:65]
	v_add_u32_e32 v32, 0xa0, v162
	s_waitcnt lgkmcnt(0)
	v_ashrrev_i32_e32 v33, 31, v32
	v_lshlrev_b64 v[34:35], 12, v[32:33]
	v_lshl_add_u64 v[34:35], s[20:21], 0, v[34:35]
	v_lshl_add_u64 v[38:39], v[160:161], 1, v[34:35]
	s_waitcnt vmcnt(15)
	v_lshlrev_b32_e32 v40, 16, v236
	v_and_b32_e32 v41, 0xffff0000, v236
	v_lshlrev_b32_e32 v34, 16, v237
	v_and_b32_e32 v35, 0xffff0000, v237
	v_lshlrev_b32_e32 v42, 16, v238
	v_and_b32_e32 v43, 0xffff0000, v238
	v_lshlrev_b32_e32 v36, 16, v239
	v_and_b32_e32 v37, 0xffff0000, v239
	v_pk_add_f32 v[34:35], v[30:31], v[34:35]
	v_pk_add_f32 v[40:41], v[28:29], v[40:41]
	v_pk_add_f32 v[36:37], v[26:27], v[36:37]
	v_pk_add_f32 v[42:43], v[24:25], v[42:43]
	v_cvt_pk_bf16_f32 v24, v40, v41
	v_cvt_pk_bf16_f32 v25, v34, v35
	v_mul_f32_e32 v41, v41, v41
	v_cvt_pk_bf16_f32 v26, v42, v43
	v_cvt_pk_bf16_f32 v27, v36, v37
	v_mul_f32_e32 v35, v35, v35
	v_mul_f32_e32 v43, v43, v43
	v_fmac_f32_e32 v41, v40, v40
	v_fmac_f32_e32 v35, v34, v34
	v_mul_f32_e32 v37, v37, v37
	v_fmac_f32_e32 v43, v42, v42
	v_add_f32_e32 v34, v41, v35
	v_fmac_f32_e32 v37, v36, v36
	v_add_f32_e32 v34, v43, v34
	v_add_f32_e32 v40, v37, v34
	global_store_dwordx4 v[38:39], v[24:27], off
	s_waitcnt vmcnt(15)
	v_lshlrev_b32_e32 v34, 16, v240
	v_and_b32_e32 v35, 0xffff0000, v240
	v_lshlrev_b32_e32 v28, 16, v241
	v_and_b32_e32 v29, 0xffff0000, v241
	v_lshlrev_b32_e32 v36, 16, v242
	v_and_b32_e32 v37, 0xffff0000, v242
	v_lshlrev_b32_e32 v30, 16, v243
	v_and_b32_e32 v31, 0xffff0000, v243
	v_pk_add_f32 v[22:23], v[22:23], v[28:29]
	v_pk_add_f32 v[20:21], v[20:21], v[34:35]
	v_pk_add_f32 v[28:29], v[18:19], v[30:31]
	v_pk_add_f32 v[30:31], v[16:17], v[36:37]
	v_mul_f32_e32 v16, v21, v21
	v_mul_f32_e32 v17, v23, v23
	v_mul_f32_e32 v18, v31, v31
	v_fmac_f32_e32 v16, v20, v20
	v_fmac_f32_e32 v17, v22, v22
	v_mul_f32_e32 v19, v29, v29
	v_fmac_f32_e32 v18, v30, v30
	v_add_f32_e32 v16, v16, v17
	v_add_f32_e32 v16, v18, v16
	v_fmac_f32_e32 v19, v28, v28
	v_add_f32_e32 v16, v19, v16
	v_add_f32_e32 v16, v40, v16
	ds_bpermute_b32 v17, v120, v16
	v_cvt_pk_bf16_f32 v18, v20, v21
	v_cvt_pk_bf16_f32 v19, v22, v23
	v_cvt_pk_bf16_f32 v20, v30, v31
	v_cvt_pk_bf16_f32 v21, v28, v29
	s_waitcnt lgkmcnt(0)
	v_add_f32_e32 v16, v16, v17
	ds_bpermute_b32 v17, v114, v16
	global_store_dwordx4 v[38:39], v[18:21], off offset:256
	s_and_saveexec_b64 s[64:65], s[6:7]
	s_cbranch_execz .LBB0_1538
	v_lshl_add_u64 v[18:19], v[32:33], 2, s[18:19]
	s_waitcnt lgkmcnt(0)
	v_add_f32_e32 v16, v16, v17
	global_atomic_add_f32 v[18:19], v16, off
.LBB0_1538:
	s_or_b64 exec, exec, s[64:65]
	v_add_u32_e32 v16, 0xb0, v162
	s_waitcnt lgkmcnt(0)
	v_ashrrev_i32_e32 v17, 31, v16
	v_lshlrev_b64 v[18:19], 12, v[16:17]
	v_lshl_add_u64 v[18:19], s[20:21], 0, v[18:19]
	v_lshl_add_u64 v[22:23], v[160:161], 1, v[18:19]
	s_waitcnt vmcnt(15)
	v_lshlrev_b32_e32 v24, 16, v244
	v_and_b32_e32 v25, 0xffff0000, v244
	v_lshlrev_b32_e32 v18, 16, v245
	v_and_b32_e32 v19, 0xffff0000, v245
	v_lshlrev_b32_e32 v26, 16, v246
	v_and_b32_e32 v27, 0xffff0000, v246
	v_lshlrev_b32_e32 v20, 16, v247
	v_and_b32_e32 v21, 0xffff0000, v247
	v_pk_add_f32 v[18:19], v[14:15], v[18:19]
	v_pk_add_f32 v[24:25], v[12:13], v[24:25]
	v_pk_add_f32 v[20:21], v[10:11], v[20:21]
	v_pk_add_f32 v[26:27], v[8:9], v[26:27]
	v_cvt_pk_bf16_f32 v8, v24, v25
	v_cvt_pk_bf16_f32 v9, v18, v19
	v_mul_f32_e32 v25, v25, v25
	v_cvt_pk_bf16_f32 v10, v26, v27
	v_cvt_pk_bf16_f32 v11, v20, v21
	v_mul_f32_e32 v19, v19, v19
	v_mul_f32_e32 v27, v27, v27
	v_fmac_f32_e32 v25, v24, v24
	v_fmac_f32_e32 v19, v18, v18
	v_mul_f32_e32 v21, v21, v21
	v_fmac_f32_e32 v27, v26, v26
	v_add_f32_e32 v18, v25, v19
	v_fmac_f32_e32 v21, v20, v20
	v_add_f32_e32 v18, v27, v18
	v_add_f32_e32 v24, v21, v18
	global_store_dwordx4 v[22:23], v[8:11], off
	s_waitcnt vmcnt(15)
	v_lshlrev_b32_e32 v18, 16, v252
	v_and_b32_e32 v19, 0xffff0000, v252
	v_lshlrev_b32_e32 v12, 16, v253
	v_and_b32_e32 v13, 0xffff0000, v253
	v_lshlrev_b32_e32 v20, 16, v254
	v_and_b32_e32 v21, 0xffff0000, v254
	v_lshlrev_b32_e32 v14, 16, v255
	v_and_b32_e32 v15, 0xffff0000, v255
	v_pk_add_f32 v[6:7], v[6:7], v[12:13]
	v_pk_add_f32 v[4:5], v[4:5], v[18:19]
	v_pk_add_f32 v[12:13], v[2:3], v[14:15]
	v_pk_add_f32 v[14:15], v[0:1], v[20:21]
	v_mul_f32_e32 v0, v5, v5
	v_mul_f32_e32 v1, v7, v7
	v_mul_f32_e32 v2, v15, v15
	v_fmac_f32_e32 v0, v4, v4
	v_fmac_f32_e32 v1, v6, v6
	v_mul_f32_e32 v3, v13, v13
	v_fmac_f32_e32 v2, v14, v14
	v_add_f32_e32 v0, v0, v1
	v_add_f32_e32 v0, v2, v0
	v_fmac_f32_e32 v3, v12, v12
	v_add_f32_e32 v0, v3, v0
	v_add_f32_e32 v0, v24, v0
	ds_bpermute_b32 v1, v120, v0
	v_cvt_pk_bf16_f32 v2, v4, v5
	v_cvt_pk_bf16_f32 v3, v6, v7
	v_cvt_pk_bf16_f32 v4, v14, v15
	v_cvt_pk_bf16_f32 v5, v12, v13
	s_waitcnt lgkmcnt(0)
	v_add_f32_e32 v0, v0, v1
	ds_bpermute_b32 v1, v114, v0
	global_store_dwordx4 v[22:23], v[2:5], off offset:256
	s_and_saveexec_b64 s[64:65], s[6:7]
	s_cbranch_execz .LBB0_1540
	v_lshl_add_u64 v[2:3], v[16:17], 2, s[18:19]
	s_waitcnt lgkmcnt(0)
	v_add_f32_e32 v0, v0, v1
	global_atomic_add_f32 v[2:3], v0, off

; __device__ __forceinline__ unsigned cvt_pk_bf16(float lo, float hi) { unsigned r; asm volatile("v_cvt_pk_bf16_f32 %0, %1, %2" : "=v"(r) : "v"(lo), "v"(hi)); return r; }
;     __device__ __forceinline__ void row(const f32x4 (&v)[2][2], const Unit& u, int row, int wc, int fq, float) const {
;         const int col0 = u.pn * BM + wc * 32 + 8 * fq;
;         const float* rbase = (u.pm < MP / BM) ? resid_p : resid_s - (size_t)MP * DM;
;         const size_t off = (size_t)row * DM + col0; float ss = 0.f;
; #pragma unroll
;         for (int bj = 0; bj < 2; ++bj) {
;             f32x4 r0, r1;
;             if (rbf) { const u32x4 w = *(const u32x4*)(rbf + off + bj * HALF);
;                 r0 = (f32x4){__uint_as_float(w.x << 16), __uint_as_float(w.x & 0xffff0000u), __uint_as_float(w.y << 16), __uint_as_float(w.y & 0xffff0000u)};
;                 r1 = (f32x4){__uint_as_float(w.z << 16), __uint_as_float(w.z & 0xffff0000u), __uint_as_float(w.w << 16), __uint_as_float(w.w & 0xffff0000u)}; }
;             else { r0 = *(const f32x4*)(rbase + off + bj * HALF); r1 = *(const f32x4*)(rbase + off + bj * HALF + 4); }
;             const f32x4 v0 = r0 + v[bj][0] * alpha, v1 = r1 + v[bj][1] * alpha;
;             ss += (v0[0] * v0[0] + v0[1] * v0[1]) + (v0[2] * v0[2] + v0[3] * v0[3]) + (v1[0] * v1[0] + v1[1] * v1[1]) + (v1[2] * v1[2] + v1[3] * v1[3]);
;             u32x4 w; w.x = cvt_pk_bf16(v0[0], v0[1]); w.y = cvt_pk_bf16(v0[2], v0[3]); w.z = cvt_pk_bf16(v1[0], v1[1]); w.w = cvt_pk_bf16(v1[2], v1[3]);
;             *(u32x4*)(hb + off + bj * HALF) = w; }
;         ss += __shfl_xor(ss, 16); ss += __shfl_xor(ss, 32);
;         if (fq == 0) atomicAdd(rowss + row, ss);
.LBB0_1764:
	v_lshl_add_u32 v162, s96, 8, v136
	v_ashrrev_i32_e32 v163, 31, v162
	v_lshl_or_b32 v160, s95, 8, v137
	v_lshlrev_b64 v[164:165], 12, v[162:163]
	s_waitcnt lgkmcnt(0)
	v_ashrrev_i32_e32 v161, 31, v160
	v_lshl_add_u64 v[164:165], s[20:21], 0, v[164:165]
	v_lshl_add_u64 v[168:169], v[160:161], 1, v[164:165]
	global_load_dwordx4 v[188:191], v[168:169], off
	global_load_dwordx4 v[192:195], v[168:169], off offset:256
	s_mov_b64 s[98:99], 0x10000
	v_lshl_add_u64 v[248:249], v[168:169], 0, s[98:99]
	global_load_dwordx4 v[196:199], v[248:249], off
	global_load_dwordx4 v[200:203], v[248:249], off offset:256
	s_mov_b64 s[98:99], 0x20000
	v_lshl_add_u64 v[248:249], v[168:169], 0, s[98:99]
	global_load_dwordx4 v[204:207], v[248:249], off
	global_load_dwordx4 v[208:211], v[248:249], off offset:256
	s_mov_b64 s[98:99], 0x30000
	v_lshl_add_u64 v[248:249], v[168:169], 0, s[98:99]
	global_load_dwordx4 v[212:215], v[248:249], off
	global_load_dwordx4 v[216:219], v[248:249], off offset:256
	s_mov_b64 s[98:99], 0x80000
	v_lshl_add_u64 v[248:249], v[168:169], 0, s[98:99]
	global_load_dwordx4 v[220:223], v[248:249], off
	global_load_dwordx4 v[224:227], v[248:249], off offset:256
	s_mov_b64 s[98:99], 0x90000
	v_lshl_add_u64 v[248:249], v[168:169], 0, s[98:99]
	global_load_dwordx4 v[228:231], v[248:249], off
	global_load_dwordx4 v[232:235], v[248:249], off offset:256
	s_mov_b64 s[98:99], 0xa0000
	v_lshl_add_u64 v[248:249], v[168:169], 0, s[98:99]
	global_load_dwordx4 v[236:239], v[248:249], off
	global_load_dwordx4 v[240:243], v[248:249], off offset:256
	s_mov_b64 s[98:99], 0xb0000
	v_lshl_add_u64 v[248:249], v[168:169], 0, s[98:99]
	global_load_dwordx4 v[244:247], v[248:249], off
	global_load_dwordx4 v[252:255], v[248:249], off offset:256
	v_xor_b32_e32 v176, 32, v187
	s_waitcnt vmcnt(15)
	v_lshlrev_b32_e32 v170, 16, v188
	v_and_b32_e32 v171, 0xffff0000, v188
	v_lshlrev_b32_e32 v164, 16, v189
	v_and_b32_e32 v165, 0xffff0000, v189
	v_lshlrev_b32_e32 v172, 16, v190
	v_and_b32_e32 v173, 0xffff0000, v190
	v_lshlrev_b32_e32 v166, 16, v191
	v_and_b32_e32 v167, 0xffff0000, v191
	v_pk_fma_f32 v[126:127], v[126:127], 0.5, v[164:165] op_sel_hi:[1,0,1]
	v_pk_fma_f32 v[170:171], v[124:125], 0.5, v[170:171] op_sel_hi:[1,0,1]
	v_pk_fma_f32 v[174:175], v[122:123], 0.5, v[166:167] op_sel_hi:[1,0,1]
	v_pk_fma_f32 v[172:173], v[120:121], 0.5, v[172:173] op_sel_hi:[1,0,1]
	v_cvt_pk_bf16_f32 v122, v170, v171
	v_cvt_pk_bf16_f32 v123, v126, v127
	v_mul_f32_e32 v171, v171, v171
	v_cvt_pk_bf16_f32 v124, v172, v173
	v_cvt_pk_bf16_f32 v125, v174, v175
	v_mul_f32_e32 v127, v127, v127
	v_mul_f32_e32 v173, v173, v173
	v_fmac_f32_e32 v171, v170, v170
	v_fmac_f32_e32 v127, v126, v126
	v_mul_f32_e32 v175, v175, v175
	v_fmac_f32_e32 v173, v172, v172
	v_add_f32_e32 v126, v171, v127
	v_fmac_f32_e32 v175, v174, v174
	v_add_f32_e32 v126, v173, v126
	v_add_f32_e32 v172, v175, v126
	v_and_b32_e32 v121, 64, v187
	v_xor_b32_e32 v120, 16, v187
	v_add_u32_e32 v121, 64, v121
	v_cmp_lt_i32_e32 vcc, v120, v121
	global_store_dwordx4 v[168:169], v[122:125], off
	s_waitcnt vmcnt(15)
	v_lshlrev_b32_e32 v126, 16, v192
	v_and_b32_e32 v127, 0xffff0000, v192
	v_lshlrev_b32_e32 v164, 16, v193
	v_and_b32_e32 v165, 0xffff0000, v193
	v_lshlrev_b32_e32 v170, 16, v194
	v_and_b32_e32 v171, 0xffff0000, v194
	v_pk_fma_f32 v[118:119], v[118:119], 0.5, v[164:165] op_sel_hi:[1,0,1]
	v_pk_fma_f32 v[116:117], v[116:117], 0.5, v[126:127] op_sel_hi:[1,0,1]
	v_lshlrev_b32_e32 v166, 16, v195
	v_and_b32_e32 v167, 0xffff0000, v195
	v_pk_fma_f32 v[164:165], v[112:113], 0.5, v[170:171] op_sel_hi:[1,0,1]
	v_mul_f32_e32 v112, v117, v117
	v_mul_f32_e32 v113, v119, v119
	v_pk_fma_f32 v[126:127], v[114:115], 0.5, v[166:167] op_sel_hi:[1,0,1]
	v_mul_f32_e32 v114, v165, v165
	v_fmac_f32_e32 v112, v116, v116
	v_fmac_f32_e32 v113, v118, v118
	v_mul_f32_e32 v115, v127, v127
	v_fmac_f32_e32 v114, v164, v164
	v_add_f32_e32 v112, v112, v113
	v_fmac_f32_e32 v115, v126, v126
	v_add_f32_e32 v112, v114, v112
	v_cndmask_b32_e32 v120, v187, v120, vcc
	v_add_f32_e32 v112, v115, v112
	v_lshlrev_b32_e32 v120, 2, v120
	v_add_f32_e32 v112, v172, v112
	ds_bpermute_b32 v113, v120, v112
	v_cmp_lt_i32_e32 vcc, v176, v121
	v_cvt_pk_bf16_f32 v116, v116, v117
	v_cvt_pk_bf16_f32 v117, v118, v119
	v_cvt_pk_bf16_f32 v118, v164, v165
	s_waitcnt lgkmcnt(0)
	v_add_f32_e32 v112, v112, v113
	v_cvt_pk_bf16_f32 v119, v126, v127
	v_cndmask_b32_e32 v114, v187, v176, vcc
	v_lshlrev_b32_e32 v114, 2, v114
	ds_bpermute_b32 v113, v114, v112
	global_store_dwordx4 v[168:169], v[116:119], off offset:256
	s_and_saveexec_b64 s[60:61], s[6:7]
	s_cbranch_execz .LBB0_1766
	v_lshl_add_u64 v[116:117], v[162:163], 2, s[18:19]
	s_waitcnt lgkmcnt(0)
	v_add_f32_e32 v112, v112, v113
	global_atomic_add_f32 v[116:117], v112, off
; __device__ __forceinline__ unsigned cvt_pk_bf16(float lo, float hi) { unsigned r; asm volatile("v_cvt_pk_bf16_f32 %0, %1, %2" : "=v"(r) : "v"(lo), "v"(hi)); return r; }
;     __device__ __forceinline__ void row(const f32x4 (&v)[2][2], const Unit& u, int row, int wc, int fq, float) const {
;         const int col0 = u.pn * BM + wc * 32 + 8 * fq;
;         const float* rbase = (u.pm < MP / BM) ? resid_p : resid_s - (size_t)MP * DM;
;         const size_t off = (size_t)row * DM + col0; float ss = 0.f;
; #pragma unroll
;         for (int bj = 0; bj < 2; ++bj) {
;             f32x4 r0, r1;
;             if (rbf) { const u32x4 w = *(const u32x4*)(rbf + off + bj * HALF);
;                 r0 = (f32x4){__uint_as_float(w.x << 16), __uint_as_float(w.x & 0xffff0000u), __uint_as_float(w.y << 16), __uint_as_float(w.y & 0xffff0000u)};
;                 r1 = (f32x4){__uint_as_float(w.z << 16), __uint_as_float(w.z & 0xffff0000u), __uint_as_float(w.w << 16), __uint_as_float(w.w & 0xffff0000u)}; }
;             else { r0 = *(const f32x4*)(rbase + off + bj * HALF); r1 = *(const f32x4*)(rbase + off + bj * HALF + 4); }
;             const f32x4 v0 = r0 + v[bj][0] * alpha, v1 = r1 + v[bj][1] * alpha;
;             ss += (v0[0] * v0[0] + v0[1] * v0[1]) + (v0[2] * v0[2] + v0[3] * v0[3]) + (v1[0] * v1[0] + v1[1] * v1[1]) + (v1[2] * v1[2] + v1[3] * v1[3]);
;             u32x4 w; w.x = cvt_pk_bf16(v0[0], v0[1]); w.y = cvt_pk_bf16(v0[2], v0[3]); w.z = cvt_pk_bf16(v1[0], v1[1]); w.w = cvt_pk_bf16(v1[2], v1[3]);
;             *(u32x4*)(hb + off + bj * HALF) = w; }
;         ss += __shfl_xor(ss, 16); ss += __shfl_xor(ss, 32);
;         if (fq == 0) atomicAdd(rowss + row, ss);
.LBB0_1766:
	s_or_b64 exec, exec, s[60:61]
	v_or_b32_e32 v112, 16, v162
	s_waitcnt lgkmcnt(0)
	v_ashrrev_i32_e32 v113, 31, v112
	v_lshlrev_b64 v[116:117], 12, v[112:113]
	v_lshl_add_u64 v[116:117], s[20:21], 0, v[116:117]
	v_lshl_add_u64 v[122:123], v[160:161], 1, v[116:117]
	s_waitcnt vmcnt(15)
	v_lshlrev_b32_e32 v124, 16, v196
	v_and_b32_e32 v125, 0xffff0000, v196
	v_lshlrev_b32_e32 v116, 16, v197
	v_and_b32_e32 v117, 0xffff0000, v197
	v_lshlrev_b32_e32 v126, 16, v198
	v_and_b32_e32 v127, 0xffff0000, v198
	v_lshlrev_b32_e32 v118, 16, v199
	v_and_b32_e32 v119, 0xffff0000, v199
	v_pk_fma_f32 v[116:117], v[110:111], 0.5, v[116:117] op_sel_hi:[1,0,1]
	v_pk_fma_f32 v[124:125], v[108:109], 0.5, v[124:125] op_sel_hi:[1,0,1]
	v_pk_fma_f32 v[118:119], v[106:107], 0.5, v[118:119] op_sel_hi:[1,0,1]
	v_pk_fma_f32 v[126:127], v[104:105], 0.5, v[126:127] op_sel_hi:[1,0,1]
	v_cvt_pk_bf16_f32 v104, v124, v125
	v_cvt_pk_bf16_f32 v105, v116, v117
	v_mul_f32_e32 v115, v125, v125
	v_cvt_pk_bf16_f32 v106, v126, v127
	v_cvt_pk_bf16_f32 v107, v118, v119
	v_mul_f32_e32 v117, v117, v117
	v_mul_f32_e32 v121, v127, v127
	v_fmac_f32_e32 v115, v124, v124
	v_fmac_f32_e32 v117, v116, v116
	v_mul_f32_e32 v119, v119, v119
	v_fmac_f32_e32 v121, v126, v126
	v_add_f32_e32 v115, v115, v117
	v_fmac_f32_e32 v119, v118, v118
	v_add_f32_e32 v115, v121, v115
	v_add_f32_e32 v115, v119, v115
	global_store_dwordx4 v[122:123], v[104:107], off
	s_waitcnt vmcnt(15)
	v_lshlrev_b32_e32 v116, 16, v200
	v_and_b32_e32 v117, 0xffff0000, v200
	v_lshlrev_b32_e32 v108, 16, v201
	v_and_b32_e32 v109, 0xffff0000, v201
	v_lshlrev_b32_e32 v118, 16, v202
	v_and_b32_e32 v119, 0xffff0000, v202
	v_lshlrev_b32_e32 v110, 16, v203
	v_and_b32_e32 v111, 0xffff0000, v203
	v_pk_fma_f32 v[102:103], v[102:103], 0.5, v[108:109] op_sel_hi:[1,0,1]
	v_pk_fma_f32 v[100:101], v[100:101], 0.5, v[116:117] op_sel_hi:[1,0,1]
	v_pk_fma_f32 v[108:109], v[98:99], 0.5, v[110:111] op_sel_hi:[1,0,1]
	v_pk_fma_f32 v[110:111], v[96:97], 0.5, v[118:119] op_sel_hi:[1,0,1]
	v_mul_f32_e32 v96, v101, v101
	v_mul_f32_e32 v97, v103, v103
	v_mul_f32_e32 v98, v111, v111
	v_fmac_f32_e32 v96, v100, v100
	v_fmac_f32_e32 v97, v102, v102
	v_mul_f32_e32 v99, v109, v109
	v_fmac_f32_e32 v98, v110, v110
	v_add_f32_e32 v96, v96, v97
	v_add_f32_e32 v96, v98, v96
	v_fmac_f32_e32 v99, v108, v108
	v_add_f32_e32 v96, v99, v96
	v_add_f32_e32 v96, v115, v96
	ds_bpermute_b32 v97, v120, v96
	v_cvt_pk_bf16_f32 v98, v100, v101
	v_cvt_pk_bf16_f32 v99, v102, v103
	v_cvt_pk_bf16_f32 v100, v110, v111
	v_cvt_pk_bf16_f32 v101, v108, v109
	s_waitcnt lgkmcnt(0)
	v_add_f32_e32 v96, v96, v97
	ds_bpermute_b32 v97, v114, v96
	global_store_dwordx4 v[122:123], v[98:101], off offset:256
	s_and_saveexec_b64 s[60:61], s[6:7]
	s_cbranch_execz .LBB0_1768
	v_lshl_add_u64 v[98:99], v[112:113], 2, s[18:19]
	s_waitcnt lgkmcnt(0)
	v_add_f32_e32 v96, v96, v97
	global_atomic_add_f32 v[98:99], v96, off
.LBB0_1768:
	s_or_b64 exec, exec, s[60:61]
	v_or_b32_e32 v96, 32, v162
	s_waitcnt lgkmcnt(0)
	v_ashrrev_i32_e32 v97, 31, v96
	v_lshlrev_b64 v[98:99], 12, v[96:97]
	v_lshl_add_u64 v[98:99], s[20:21], 0, v[98:99]
	v_lshl_add_u64 v[102:103], v[160:161], 1, v[98:99]
	s_waitcnt vmcnt(15)
	v_lshlrev_b32_e32 v104, 16, v204
	v_and_b32_e32 v105, 0xffff0000, v204
	v_lshlrev_b32_e32 v98, 16, v205
	v_and_b32_e32 v99, 0xffff0000, v205
	v_lshlrev_b32_e32 v106, 16, v206
	v_and_b32_e32 v107, 0xffff0000, v206
	v_lshlrev_b32_e32 v100, 16, v207
	v_and_b32_e32 v101, 0xffff0000, v207
	v_pk_fma_f32 v[98:99], v[94:95], 0.5, v[98:99] op_sel_hi:[1,0,1]
	v_pk_fma_f32 v[104:105], v[92:93], 0.5, v[104:105] op_sel_hi:[1,0,1]
	v_pk_fma_f32 v[100:101], v[90:91], 0.5, v[100:101] op_sel_hi:[1,0,1]
	v_pk_fma_f32 v[106:107], v[88:89], 0.5, v[106:107] op_sel_hi:[1,0,1]
	v_cvt_pk_bf16_f32 v88, v104, v105
	v_cvt_pk_bf16_f32 v89, v98, v99
	v_mul_f32_e32 v105, v105, v105
	v_cvt_pk_bf16_f32 v90, v106, v107
	v_cvt_pk_bf16_f32 v91, v100, v101
	v_mul_f32_e32 v99, v99, v99
	v_mul_f32_e32 v107, v107, v107
	v_fmac_f32_e32 v105, v104, v104
	v_fmac_f32_e32 v99, v98, v98
	v_mul_f32_e32 v101, v101, v101
	v_fmac_f32_e32 v107, v106, v106
	v_add_f32_e32 v98, v105, v99
	v_fmac_f32_e32 v101, v100, v100
	v_add_f32_e32 v98, v107, v98
	v_add_f32_e32 v104, v101, v98
	global_store_dwordx4 v[102:103], v[88:91], off
	s_waitcnt vmcnt(15)
	v_lshlrev_b32_e32 v98, 16, v208
	v_and_b32_e32 v99, 0xffff0000, v208
	v_lshlrev_b32_e32 v92, 16, v209
	v_and_b32_e32 v93, 0xffff0000, v209
	v_lshlrev_b32_e32 v100, 16, v210
	v_and_b32_e32 v101, 0xffff0000, v210
	v_lshlrev_b32_e32 v94, 16, v211
	v_and_b32_e32 v95, 0xffff0000, v211
	v_pk_fma_f32 v[86:87], v[86:87], 0.5, v[92:93] op_sel_hi:[1,0,1]
	v_pk_fma_f32 v[84:85], v[84:85], 0.5, v[98:99] op_sel_hi:[1,0,1]
	v_pk_fma_f32 v[92:93], v[82:83], 0.5, v[94:95] op_sel_hi:[1,0,1]
	v_pk_fma_f32 v[94:95], v[80:81], 0.5, v[100:101] op_sel_hi:[1,0,1]
	v_mul_f32_e32 v80, v85, v85
	v_mul_f32_e32 v81, v87, v87
	v_mul_f32_e32 v82, v95, v95
	v_fmac_f32_e32 v80, v84, v84
	v_fmac_f32_e32 v81, v86, v86
	v_mul_f32_e32 v83, v93, v93
	v_fmac_f32_e32 v82, v94, v94
	v_add_f32_e32 v80, v80, v81
	v_add_f32_e32 v80, v82, v80
	v_fmac_f32_e32 v83, v92, v92
	v_add_f32_e32 v80, v83, v80
	v_add_f32_e32 v80, v104, v80
	ds_bpermute_b32 v81, v120, v80
	v_cvt_pk_bf16_f32 v82, v84, v85
	v_cvt_pk_bf16_f32 v83, v86, v87
	v_cvt_pk_bf16_f32 v84, v94, v95
	v_cvt_pk_bf16_f32 v85, v92, v93
	s_waitcnt lgkmcnt(0)
	v_add_f32_e32 v80, v80, v81
	ds_bpermute_b32 v81, v114, v80
	global_store_dwordx4 v[102:103], v[82:85], off offset:256
	s_and_saveexec_b64 s[60:61], s[6:7]
	s_cbranch_execz .LBB0_1770
	v_lshl_add_u64 v[82:83], v[96:97], 2, s[18:19]
	s_waitcnt lgkmcnt(0)
	v_add_f32_e32 v80, v80, v81
	global_atomic_add_f32 v[82:83], v80, off
; __device__ __forceinline__ unsigned cvt_pk_bf16(float lo, float hi) { unsigned r; asm volatile("v_cvt_pk_bf16_f32 %0, %1, %2" : "=v"(r) : "v"(lo), "v"(hi)); return r; }
;     __device__ __forceinline__ void row(const f32x4 (&v)[2][2], const Unit& u, int row, int wc, int fq, float) const {
;         const int col0 = u.pn * BM + wc * 32 + 8 * fq;
;         const float* rbase = (u.pm < MP / BM) ? resid_p : resid_s - (size_t)MP * DM;
;         const size_t off = (size_t)row * DM + col0; float ss = 0.f;
; #pragma unroll
;         for (int bj = 0; bj < 2; ++bj) {
;             f32x4 r0, r1;
;             if (rbf) { const u32x4 w = *(const u32x4*)(rbf + off + bj * HALF);
;                 r0 = (f32x4){__uint_as_float(w.x << 16), __uint_as_float(w.x & 0xffff0000u), __uint_as_float(w.y << 16), __uint_as_float(w.y & 0xffff0000u)};
;                 r1 = (f32x4){__uint_as_float(w.z << 16), __uint_as_float(w.z & 0xffff0000u), __uint_as_float(w.w << 16), __uint_as_float(w.w & 0xffff0000u)}; }
;             else { r0 = *(const f32x4*)(rbase + off + bj * HALF); r1 = *(const f32x4*)(rbase + off + bj * HALF + 4); }
;             const f32x4 v0 = r0 + v[bj][0] * alpha, v1 = r1 + v[bj][1] * alpha;
;             ss += (v0[0] * v0[0] + v0[1] * v0[1]) + (v0[2] * v0[2] + v0[3] * v0[3]) + (v1[0] * v1[0] + v1[1] * v1[1]) + (v1[2] * v1[2] + v1[3] * v1[3]);
;             u32x4 w; w.x = cvt_pk_bf16(v0[0], v0[1]); w.y = cvt_pk_bf16(v0[2], v0[3]); w.z = cvt_pk_bf16(v1[0], v1[1]); w.w = cvt_pk_bf16(v1[2], v1[3]);
;             *(u32x4*)(hb + off + bj * HALF) = w; }
;         ss += __shfl_xor(ss, 16); ss += __shfl_xor(ss, 32);
;         if (fq == 0) atomicAdd(rowss + row, ss);
.LBB0_1770:
	s_or_b64 exec, exec, s[60:61]
	v_or_b32_e32 v80, 48, v162
	s_waitcnt lgkmcnt(0)
	v_ashrrev_i32_e32 v81, 31, v80
	v_lshlrev_b64 v[82:83], 12, v[80:81]
	v_lshl_add_u64 v[82:83], s[20:21], 0, v[82:83]
	v_lshl_add_u64 v[86:87], v[160:161], 1, v[82:83]
	s_waitcnt vmcnt(15)
	v_lshlrev_b32_e32 v88, 16, v212
	v_and_b32_e32 v89, 0xffff0000, v212
	v_lshlrev_b32_e32 v82, 16, v213
	v_and_b32_e32 v83, 0xffff0000, v213
	v_lshlrev_b32_e32 v90, 16, v214
	v_and_b32_e32 v91, 0xffff0000, v214
	v_lshlrev_b32_e32 v84, 16, v215
	v_and_b32_e32 v85, 0xffff0000, v215
	v_pk_fma_f32 v[82:83], v[78:79], 0.5, v[82:83] op_sel_hi:[1,0,1]
	v_pk_fma_f32 v[88:89], v[76:77], 0.5, v[88:89] op_sel_hi:[1,0,1]
	v_pk_fma_f32 v[84:85], v[74:75], 0.5, v[84:85] op_sel_hi:[1,0,1]
	v_pk_fma_f32 v[90:91], v[72:73], 0.5, v[90:91] op_sel_hi:[1,0,1]
	v_cvt_pk_bf16_f32 v72, v88, v89
	v_cvt_pk_bf16_f32 v73, v82, v83
	v_mul_f32_e32 v89, v89, v89
	v_cvt_pk_bf16_f32 v74, v90, v91
	v_cvt_pk_bf16_f32 v75, v84, v85
	v_mul_f32_e32 v83, v83, v83
	v_mul_f32_e32 v91, v91, v91
	v_fmac_f32_e32 v89, v88, v88
	v_fmac_f32_e32 v83, v82, v82
	v_mul_f32_e32 v85, v85, v85
	v_fmac_f32_e32 v91, v90, v90
	v_add_f32_e32 v82, v89, v83
	v_fmac_f32_e32 v85, v84, v84
	v_add_f32_e32 v82, v91, v82
	v_add_f32_e32 v88, v85, v82
	global_store_dwordx4 v[86:87], v[72:75], off
	s_waitcnt vmcnt(15)
	v_lshlrev_b32_e32 v82, 16, v216
	v_and_b32_e32 v83, 0xffff0000, v216
	v_lshlrev_b32_e32 v76, 16, v217
	v_and_b32_e32 v77, 0xffff0000, v217
	v_lshlrev_b32_e32 v84, 16, v218
	v_and_b32_e32 v85, 0xffff0000, v218
	v_lshlrev_b32_e32 v78, 16, v219
	v_and_b32_e32 v79, 0xffff0000, v219
	v_pk_fma_f32 v[70:71], v[70:71], 0.5, v[76:77] op_sel_hi:[1,0,1]
	v_pk_fma_f32 v[68:69], v[68:69], 0.5, v[82:83] op_sel_hi:[1,0,1]
	v_pk_fma_f32 v[76:77], v[66:67], 0.5, v[78:79] op_sel_hi:[1,0,1]
	v_pk_fma_f32 v[78:79], v[64:65], 0.5, v[84:85] op_sel_hi:[1,0,1]
	v_mul_f32_e32 v64, v69, v69
	v_mul_f32_e32 v65, v71, v71
	v_mul_f32_e32 v66, v79, v79
	v_fmac_f32_e32 v64, v68, v68
	v_fmac_f32_e32 v65, v70, v70
	v_mul_f32_e32 v67, v77, v77
	v_fmac_f32_e32 v66, v78, v78
	v_add_f32_e32 v64, v64, v65
	v_add_f32_e32 v64, v66, v64
	v_fmac_f32_e32 v67, v76, v76
	v_add_f32_e32 v64, v67, v64
	v_add_f32_e32 v64, v88, v64
	ds_bpermute_b32 v65, v120, v64
	v_cvt_pk_bf16_f32 v66, v68, v69
	v_cvt_pk_bf16_f32 v67, v70, v71
	v_cvt_pk_bf16_f32 v68, v78, v79
	v_cvt_pk_bf16_f32 v69, v76, v77
	s_waitcnt lgkmcnt(0)
	v_add_f32_e32 v64, v64, v65
	ds_bpermute_b32 v65, v114, v64
	global_store_dwordx4 v[86:87], v[66:69], off offset:256
	s_and_saveexec_b64 s[60:61], s[6:7]
	s_cbranch_execz .LBB0_1772
	v_lshl_add_u64 v[66:67], v[80:81], 2, s[18:19]
	s_waitcnt lgkmcnt(0)
	v_add_f32_e32 v64, v64, v65
	global_atomic_add_f32 v[66:67], v64, off
.LBB0_1772:
	s_or_b64 exec, exec, s[60:61]
	v_add_u32_e32 v64, 0x80, v162
	s_waitcnt lgkmcnt(0)
	v_ashrrev_i32_e32 v65, 31, v64
	v_lshlrev_b64 v[66:67], 12, v[64:65]
	v_lshl_add_u64 v[66:67], s[20:21], 0, v[66:67]
	v_lshl_add_u64 v[70:71], v[160:161], 1, v[66:67]
	s_waitcnt vmcnt(15)
	v_lshlrev_b32_e32 v72, 16, v220
	v_and_b32_e32 v73, 0xffff0000, v220
	v_lshlrev_b32_e32 v66, 16, v221
	v_and_b32_e32 v67, 0xffff0000, v221
	v_lshlrev_b32_e32 v74, 16, v222
	v_and_b32_e32 v75, 0xffff0000, v222
	v_lshlrev_b32_e32 v68, 16, v223
	v_and_b32_e32 v69, 0xffff0000, v223
	v_pk_fma_f32 v[66:67], v[62:63], 0.5, v[66:67] op_sel_hi:[1,0,1]
	v_pk_fma_f32 v[72:73], v[60:61], 0.5, v[72:73] op_sel_hi:[1,0,1]
	v_pk_fma_f32 v[68:69], v[58:59], 0.5, v[68:69] op_sel_hi:[1,0,1]
	v_pk_fma_f32 v[74:75], v[56:57], 0.5, v[74:75] op_sel_hi:[1,0,1]
	v_cvt_pk_bf16_f32 v56, v72, v73
	v_cvt_pk_bf16_f32 v57, v66, v67
	v_mul_f32_e32 v73, v73, v73
	v_cvt_pk_bf16_f32 v58, v74, v75
	v_cvt_pk_bf16_f32 v59, v68, v69
	v_mul_f32_e32 v67, v67, v67
	v_mul_f32_e32 v75, v75, v75
	v_fmac_f32_e32 v73, v72, v72
	v_fmac_f32_e32 v67, v66, v66
	v_mul_f32_e32 v69, v69, v69
	v_fmac_f32_e32 v75, v74, v74
	v_add_f32_e32 v66, v73, v67
	v_fmac_f32_e32 v69, v68, v68
	v_add_f32_e32 v66, v75, v66
	v_add_f32_e32 v72, v69, v66
	global_store_dwordx4 v[70:71], v[56:59], off
	s_waitcnt vmcnt(15)
	v_lshlrev_b32_e32 v66, 16, v224
	v_and_b32_e32 v67, 0xffff0000, v224
	v_lshlrev_b32_e32 v60, 16, v225
	v_and_b32_e32 v61, 0xffff0000, v225
	v_lshlrev_b32_e32 v68, 16, v226
	v_and_b32_e32 v69, 0xffff0000, v226
	v_lshlrev_b32_e32 v62, 16, v227
	v_and_b32_e32 v63, 0xffff0000, v227
	v_pk_fma_f32 v[54:55], v[54:55], 0.5, v[60:61] op_sel_hi:[1,0,1]
	v_pk_fma_f32 v[52:53], v[52:53], 0.5, v[66:67] op_sel_hi:[1,0,1]
	v_pk_fma_f32 v[60:61], v[50:51], 0.5, v[62:63] op_sel_hi:[1,0,1]
	v_pk_fma_f32 v[62:63], v[48:49], 0.5, v[68:69] op_sel_hi:[1,0,1]
	v_mul_f32_e32 v48, v53, v53
	v_mul_f32_e32 v49, v55, v55
	v_mul_f32_e32 v50, v63, v63
	v_fmac_f32_e32 v48, v52, v52
	v_fmac_f32_e32 v49, v54, v54
	v_mul_f32_e32 v51, v61, v61
	v_fmac_f32_e32 v50, v62, v62
	v_add_f32_e32 v48, v48, v49
	v_add_f32_e32 v48, v50, v48
	v_fmac_f32_e32 v51, v60, v60
	v_add_f32_e32 v48, v51, v48
	v_add_f32_e32 v48, v72, v48
	ds_bpermute_b32 v49, v120, v48
	v_cvt_pk_bf16_f32 v50, v52, v53
	v_cvt_pk_bf16_f32 v51, v54, v55
	v_cvt_pk_bf16_f32 v52, v62, v63
	v_cvt_pk_bf16_f32 v53, v60, v61
	s_waitcnt lgkmcnt(0)
	v_add_f32_e32 v48, v48, v49
	ds_bpermute_b32 v49, v114, v48
	global_store_dwordx4 v[70:71], v[50:53], off offset:256
	s_and_saveexec_b64 s[60:61], s[6:7]
	s_cbranch_execz .LBB0_1774
	v_lshl_add_u64 v[50:51], v[64:65], 2, s[18:19]
	s_waitcnt lgkmcnt(0)
	v_add_f32_e32 v48, v48, v49
	global_atomic_add_f32 v[50:51], v48, off
; __device__ __forceinline__ unsigned cvt_pk_bf16(float lo, float hi) { unsigned r; asm volatile("v_cvt_pk_bf16_f32 %0, %1, %2" : "=v"(r) : "v"(lo), "v"(hi)); return r; }
;     __device__ __forceinline__ void row(const f32x4 (&v)[2][2], const Unit& u, int row, int wc, int fq, float) const {
;         const int col0 = u.pn * BM + wc * 32 + 8 * fq;
;         const float* rbase = (u.pm < MP / BM) ? resid_p : resid_s - (size_t)MP * DM;
;         const size_t off = (size_t)row * DM + col0; float ss = 0.f;
; #pragma unroll
;         for (int bj = 0; bj < 2; ++bj) {
;             f32x4 r0, r1;
;             if (rbf) { const u32x4 w = *(const u32x4*)(rbf + off + bj * HALF);
;                 r0 = (f32x4){__uint_as_float(w.x << 16), __uint_as_float(w.x & 0xffff0000u), __uint_as_float(w.y << 16), __uint_as_float(w.y & 0xffff0000u)};
;                 r1 = (f32x4){__uint_as_float(w.z << 16), __uint_as_float(w.z & 0xffff0000u), __uint_as_float(w.w << 16), __uint_as_float(w.w & 0xffff0000u)}; }
;             else { r0 = *(const f32x4*)(rbase + off + bj * HALF); r1 = *(const f32x4*)(rbase + off + bj * HALF + 4); }
;             const f32x4 v0 = r0 + v[bj][0] * alpha, v1 = r1 + v[bj][1] * alpha;
;             ss += (v0[0] * v0[0] + v0[1] * v0[1]) + (v0[2] * v0[2] + v0[3] * v0[3]) + (v1[0] * v1[0] + v1[1] * v1[1]) + (v1[2] * v1[2] + v1[3] * v1[3]);
;             u32x4 w; w.x = cvt_pk_bf16(v0[0], v0[1]); w.y = cvt_pk_bf16(v0[2], v0[3]); w.z = cvt_pk_bf16(v1[0], v1[1]); w.w = cvt_pk_bf16(v1[2], v1[3]);
;             *(u32x4*)(hb + off + bj * HALF) = w; }
;         ss += __shfl_xor(ss, 16); ss += __shfl_xor(ss, 32);
;         if (fq == 0) atomicAdd(rowss + row, ss);
.LBB0_1774:
	s_or_b64 exec, exec, s[60:61]
	v_add_u32_e32 v48, 0x90, v162
	s_waitcnt lgkmcnt(0)
	v_ashrrev_i32_e32 v49, 31, v48
	v_lshlrev_b64 v[50:51], 12, v[48:49]
	v_lshl_add_u64 v[50:51], s[20:21], 0, v[50:51]
	v_lshl_add_u64 v[54:55], v[160:161], 1, v[50:51]
	s_waitcnt vmcnt(15)
	v_lshlrev_b32_e32 v56, 16, v228
	v_and_b32_e32 v57, 0xffff0000, v228
	v_lshlrev_b32_e32 v50, 16, v229
	v_and_b32_e32 v51, 0xffff0000, v229
	v_lshlrev_b32_e32 v58, 16, v230
	v_and_b32_e32 v59, 0xffff0000, v230
	v_lshlrev_b32_e32 v52, 16, v231
	v_and_b32_e32 v53, 0xffff0000, v231
	v_pk_fma_f32 v[50:51], v[46:47], 0.5, v[50:51] op_sel_hi:[1,0,1]
	v_pk_fma_f32 v[56:57], v[44:45], 0.5, v[56:57] op_sel_hi:[1,0,1]
	v_pk_fma_f32 v[52:53], v[42:43], 0.5, v[52:53] op_sel_hi:[1,0,1]
	v_pk_fma_f32 v[58:59], v[40:41], 0.5, v[58:59] op_sel_hi:[1,0,1]
	v_cvt_pk_bf16_f32 v40, v56, v57
	v_cvt_pk_bf16_f32 v41, v50, v51
	v_mul_f32_e32 v57, v57, v57
	v_cvt_pk_bf16_f32 v42, v58, v59
	v_cvt_pk_bf16_f32 v43, v52, v53
	v_mul_f32_e32 v51, v51, v51
	v_mul_f32_e32 v59, v59, v59
	v_fmac_f32_e32 v57, v56, v56
	v_fmac_f32_e32 v51, v50, v50
	v_mul_f32_e32 v53, v53, v53
	v_fmac_f32_e32 v59, v58, v58
	v_add_f32_e32 v50, v57, v51
	v_fmac_f32_e32 v53, v52, v52
	v_add_f32_e32 v50, v59, v50
	v_add_f32_e32 v56, v53, v50
	global_store_dwordx4 v[54:55], v[40:43], off
	s_waitcnt vmcnt(15)
	v_lshlrev_b32_e32 v50, 16, v232
	v_and_b32_e32 v51, 0xffff0000, v232
	v_lshlrev_b32_e32 v44, 16, v233
	v_and_b32_e32 v45, 0xffff0000, v233
	v_lshlrev_b32_e32 v52, 16, v234
	v_and_b32_e32 v53, 0xffff0000, v234
	v_lshlrev_b32_e32 v46, 16, v235
	v_and_b32_e32 v47, 0xffff0000, v235
	v_pk_fma_f32 v[38:39], v[38:39], 0.5, v[44:45] op_sel_hi:[1,0,1]
	v_pk_fma_f32 v[36:37], v[36:37], 0.5, v[50:51] op_sel_hi:[1,0,1]
	v_pk_fma_f32 v[44:45], v[34:35], 0.5, v[46:47] op_sel_hi:[1,0,1]
	v_pk_fma_f32 v[46:47], v[32:33], 0.5, v[52:53] op_sel_hi:[1,0,1]
	v_mul_f32_e32 v32, v37, v37
	v_mul_f32_e32 v33, v39, v39
	v_mul_f32_e32 v34, v47, v47
	v_fmac_f32_e32 v32, v36, v36
	v_fmac_f32_e32 v33, v38, v38
	v_mul_f32_e32 v35, v45, v45
	v_fmac_f32_e32 v34, v46, v46
	v_add_f32_e32 v32, v32, v33
	v_add_f32_e32 v32, v34, v32
	v_fmac_f32_e32 v35, v44, v44
	v_add_f32_e32 v32, v35, v32
	v_add_f32_e32 v32, v56, v32
	ds_bpermute_b32 v33, v120, v32
	v_cvt_pk_bf16_f32 v34, v36, v37
	v_cvt_pk_bf16_f32 v35, v38, v39
	v_cvt_pk_bf16_f32 v36, v46, v47
	v_cvt_pk_bf16_f32 v37, v44, v45
	s_waitcnt lgkmcnt(0)
	v_add_f32_e32 v32, v32, v33
	ds_bpermute_b32 v33, v114, v32
	global_store_dwordx4 v[54:55], v[34:37], off offset:256
	s_and_saveexec_b64 s[60:61], s[6:7]
	s_cbranch_execz .LBB0_1776
	v_lshl_add_u64 v[34:35], v[48:49], 2, s[18:19]
	s_waitcnt lgkmcnt(0)
	v_add_f32_e32 v32, v32, v33
	global_atomic_add_f32 v[34:35], v32, off
; __device__ __forceinline__ unsigned cvt_pk_bf16(float lo, float hi) { unsigned r; asm volatile("v_cvt_pk_bf16_f32 %0, %1, %2" : "=v"(r) : "v"(lo), "v"(hi)); return r; }
;     __device__ __forceinline__ void row(const f32x4 (&v)[2][2], const Unit& u, int row, int wc, int fq, float) const {
;         const int col0 = u.pn * BM + wc * 32 + 8 * fq;
;         const float* rbase = (u.pm < MP / BM) ? resid_p : resid_s - (size_t)MP * DM;
;         const size_t off = (size_t)row * DM + col0; float ss = 0.f;
; #pragma unroll
;         for (int bj = 0; bj < 2; ++bj) {
;             f32x4 r0, r1;
;             if (rbf) { const u32x4 w = *(const u32x4*)(rbf + off + bj * HALF);
;                 r0 = (f32x4){__uint_as_float(w.x << 16), __uint_as_float(w.x & 0xffff0000u), __uint_as_float(w.y << 16), __uint_as_float(w.y & 0xffff0000u)};
;                 r1 = (f32x4){__uint_as_float(w.z << 16), __uint_as_float(w.z & 0xffff0000u), __uint_as_float(w.w << 16), __uint_as_float(w.w & 0xffff0000u)}; }
;             else { r0 = *(const f32x4*)(rbase + off + bj * HALF); r1 = *(const f32x4*)(rbase + off + bj * HALF + 4); }
;             const f32x4 v0 = r0 + v[bj][0] * alpha, v1 = r1 + v[bj][1] * alpha;
;             ss += (v0[0] * v0[0] + v0[1] * v0[1]) + (v0[2] * v0[2] + v0[3] * v0[3]) + (v1[0] * v1[0] + v1[1] * v1[1]) + (v1[2] * v1[2] + v1[3] * v1[3]);
;             u32x4 w; w.x = cvt_pk_bf16(v0[0], v0[1]); w.y = cvt_pk_bf16(v0[2], v0[3]); w.z = cvt_pk_bf16(v1[0], v1[1]); w.w = cvt_pk_bf16(v1[2], v1[3]);
;             *(u32x4*)(hb + off + bj * HALF) = w; }
;         ss += __shfl_xor(ss, 16); ss += __shfl_xor(ss, 32);
;         if (fq == 0) atomicAdd(rowss + row, ss);
.LBB0_1776:
	s_or_b64 exec, exec, s[60:61]
	v_add_u32_e32 v32, 0xa0, v162
	s_waitcnt lgkmcnt(0)
	v_ashrrev_i32_e32 v33, 31, v32
	v_lshlrev_b64 v[34:35], 12, v[32:33]
	v_lshl_add_u64 v[34:35], s[20:21], 0, v[34:35]
	v_lshl_add_u64 v[38:39], v[160:161], 1, v[34:35]
	s_waitcnt vmcnt(15)
	v_lshlrev_b32_e32 v40, 16, v236
	v_and_b32_e32 v41, 0xffff0000, v236
	v_lshlrev_b32_e32 v34, 16, v237
	v_and_b32_e32 v35, 0xffff0000, v237
	v_lshlrev_b32_e32 v42, 16, v238
	v_and_b32_e32 v43, 0xffff0000, v238
	v_lshlrev_b32_e32 v36, 16, v239
	v_and_b32_e32 v37, 0xffff0000, v239
	v_pk_fma_f32 v[34:35], v[30:31], 0.5, v[34:35] op_sel_hi:[1,0,1]
	v_pk_fma_f32 v[40:41], v[28:29], 0.5, v[40:41] op_sel_hi:[1,0,1]
	v_pk_fma_f32 v[36:37], v[26:27], 0.5, v[36:37] op_sel_hi:[1,0,1]
	v_pk_fma_f32 v[42:43], v[24:25], 0.5, v[42:43] op_sel_hi:[1,0,1]
	v_cvt_pk_bf16_f32 v24, v40, v41
	v_cvt_pk_bf16_f32 v25, v34, v35
	v_mul_f32_e32 v41, v41, v41
	v_cvt_pk_bf16_f32 v26, v42, v43
	v_cvt_pk_bf16_f32 v27, v36, v37
	v_mul_f32_e32 v35, v35, v35
	v_mul_f32_e32 v43, v43, v43
	v_fmac_f32_e32 v41, v40, v40
	v_fmac_f32_e32 v35, v34, v34
	v_mul_f32_e32 v37, v37, v37
	v_fmac_f32_e32 v43, v42, v42
	v_add_f32_e32 v34, v41, v35
	v_fmac_f32_e32 v37, v36, v36
	v_add_f32_e32 v34, v43, v34
	v_add_f32_e32 v40, v37, v34
	global_store_dwordx4 v[38:39], v[24:27], off
	s_waitcnt vmcnt(15)
	v_lshlrev_b32_e32 v34, 16, v240
	v_and_b32_e32 v35, 0xffff0000, v240
	v_lshlrev_b32_e32 v28, 16, v241
	v_and_b32_e32 v29, 0xffff0000, v241
	v_lshlrev_b32_e32 v36, 16, v242
	v_and_b32_e32 v37, 0xffff0000, v242
	v_lshlrev_b32_e32 v30, 16, v243
	v_and_b32_e32 v31, 0xffff0000, v243
	v_pk_fma_f32 v[22:23], v[22:23], 0.5, v[28:29] op_sel_hi:[1,0,1]
	v_pk_fma_f32 v[20:21], v[20:21], 0.5, v[34:35] op_sel_hi:[1,0,1]
	v_pk_fma_f32 v[28:29], v[18:19], 0.5, v[30:31] op_sel_hi:[1,0,1]
	v_pk_fma_f32 v[30:31], v[16:17], 0.5, v[36:37] op_sel_hi:[1,0,1]
	v_mul_f32_e32 v16, v21, v21
	v_mul_f32_e32 v17, v23, v23
	v_mul_f32_e32 v18, v31, v31
	v_fmac_f32_e32 v16, v20, v20
	v_fmac_f32_e32 v17, v22, v22
	v_mul_f32_e32 v19, v29, v29
	v_fmac_f32_e32 v18, v30, v30
	v_add_f32_e32 v16, v16, v17
	v_add_f32_e32 v16, v18, v16
	v_fmac_f32_e32 v19, v28, v28
	v_add_f32_e32 v16, v19, v16
	v_add_f32_e32 v16, v40, v16
	ds_bpermute_b32 v17, v120, v16
	v_cvt_pk_bf16_f32 v18, v20, v21
	v_cvt_pk_bf16_f32 v19, v22, v23
	v_cvt_pk_bf16_f32 v20, v30, v31
	v_cvt_pk_bf16_f32 v21, v28, v29
	s_waitcnt lgkmcnt(0)
	v_add_f32_e32 v16, v16, v17
	ds_bpermute_b32 v17, v114, v16
	global_store_dwordx4 v[38:39], v[18:21], off offset:256
	s_and_saveexec_b64 s[60:61], s[6:7]
	s_cbranch_execz .LBB0_1778
	v_lshl_add_u64 v[18:19], v[32:33], 2, s[18:19]
	s_waitcnt lgkmcnt(0)
	v_add_f32_e32 v16, v16, v17
	global_atomic_add_f32 v[18:19], v16, off
.LBB0_1778:
	s_or_b64 exec, exec, s[60:61]
	v_add_u32_e32 v16, 0xb0, v162
	s_waitcnt lgkmcnt(0)
	v_ashrrev_i32_e32 v17, 31, v16
	v_lshlrev_b64 v[18:19], 12, v[16:17]
	v_lshl_add_u64 v[18:19], s[20:21], 0, v[18:19]
	v_lshl_add_u64 v[22:23], v[160:161], 1, v[18:19]
	s_waitcnt vmcnt(15)
	v_lshlrev_b32_e32 v24, 16, v244
	v_and_b32_e32 v25, 0xffff0000, v244
	v_lshlrev_b32_e32 v18, 16, v245
	v_and_b32_e32 v19, 0xffff0000, v245
	v_lshlrev_b32_e32 v26, 16, v246
	v_and_b32_e32 v27, 0xffff0000, v246
	v_lshlrev_b32_e32 v20, 16, v247
	v_and_b32_e32 v21, 0xffff0000, v247
	v_pk_fma_f32 v[18:19], v[14:15], 0.5, v[18:19] op_sel_hi:[1,0,1]
	v_pk_fma_f32 v[24:25], v[12:13], 0.5, v[24:25] op_sel_hi:[1,0,1]
	v_pk_fma_f32 v[20:21], v[10:11], 0.5, v[20:21] op_sel_hi:[1,0,1]
	v_pk_fma_f32 v[26:27], v[8:9], 0.5, v[26:27] op_sel_hi:[1,0,1]
	v_cvt_pk_bf16_f32 v8, v24, v25
	v_cvt_pk_bf16_f32 v9, v18, v19
	v_mul_f32_e32 v25, v25, v25
	v_cvt_pk_bf16_f32 v10, v26, v27
	v_cvt_pk_bf16_f32 v11, v20, v21
	v_mul_f32_e32 v19, v19, v19
	v_mul_f32_e32 v27, v27, v27
	v_fmac_f32_e32 v25, v24, v24
	v_fmac_f32_e32 v19, v18, v18
	v_mul_f32_e32 v21, v21, v21
	v_fmac_f32_e32 v27, v26, v26
	v_add_f32_e32 v18, v25, v19
	v_fmac_f32_e32 v21, v20, v20
	v_add_f32_e32 v18, v27, v18
	v_add_f32_e32 v24, v21, v18
	global_store_dwordx4 v[22:23], v[8:11], off
	s_waitcnt vmcnt(15)
	v_lshlrev_b32_e32 v18, 16, v252
	v_and_b32_e32 v19, 0xffff0000, v252
	v_lshlrev_b32_e32 v12, 16, v253
	v_and_b32_e32 v13, 0xffff0000, v253
	v_lshlrev_b32_e32 v20, 16, v254
	v_and_b32_e32 v21, 0xffff0000, v254
	v_lshlrev_b32_e32 v14, 16, v255
	v_and_b32_e32 v15, 0xffff0000, v255
	v_pk_fma_f32 v[6:7], v[6:7], 0.5, v[12:13] op_sel_hi:[1,0,1]
	v_pk_fma_f32 v[4:5], v[4:5], 0.5, v[18:19] op_sel_hi:[1,0,1]
	v_pk_fma_f32 v[12:13], v[2:3], 0.5, v[14:15] op_sel_hi:[1,0,1]
	v_pk_fma_f32 v[14:15], v[0:1], 0.5, v[20:21] op_sel_hi:[1,0,1]
	v_mul_f32_e32 v0, v5, v5
	v_mul_f32_e32 v1, v7, v7
	v_mul_f32_e32 v2, v15, v15
	v_fmac_f32_e32 v0, v4, v4
	v_fmac_f32_e32 v1, v6, v6
	v_mul_f32_e32 v3, v13, v13
	v_fmac_f32_e32 v2, v14, v14
	v_add_f32_e32 v0, v0, v1
	v_add_f32_e32 v0, v2, v0
	v_fmac_f32_e32 v3, v12, v12
	v_add_f32_e32 v0, v3, v0
	v_add_f32_e32 v0, v24, v0
	ds_bpermute_b32 v1, v120, v0
	v_cvt_pk_bf16_f32 v2, v4, v5
	v_cvt_pk_bf16_f32 v3, v6, v7
	v_cvt_pk_bf16_f32 v4, v14, v15
	v_cvt_pk_bf16_f32 v5, v12, v13
	s_waitcnt lgkmcnt(0)
	v_add_f32_e32 v0, v0, v1
	ds_bpermute_b32 v1, v114, v0
	global_store_dwordx4 v[22:23], v[2:5], off offset:256
	s_and_saveexec_b64 s[60:61], s[6:7]
	s_cbranch_execz .LBB0_1780
	v_lshl_add_u64 v[2:3], v[16:17], 2, s[18:19]
	s_waitcnt lgkmcnt(0)
	v_add_f32_e32 v0, v0, v1
	global_atomic_add_f32 v[2:3], v0, off

; __global__ void __launch_bounds__(512, 2) fox_fwd(Args args) {
	.amdhsa_kernel _Z7fox_fwd4Args
		.amdhsa_group_segment_fixed_size 0
		.amdhsa_private_segment_fixed_size 0
		.amdhsa_kernarg_size 448
		.amdhsa_user_sgpr_count 2
		.amdhsa_user_sgpr_dispatch_ptr 0
		.amdhsa_user_sgpr_queue_ptr 0
		.amdhsa_user_sgpr_kernarg_segment_ptr 1
		.amdhsa_user_sgpr_dispatch_id 0
		.amdhsa_user_sgpr_kernarg_preload_length 0
		.amdhsa_user_sgpr_kernarg_preload_offset 0
		.amdhsa_user_sgpr_private_segment_size 0
		.amdhsa_uses_dynamic_stack 0
		.amdhsa_enable_private_segment 0
		.amdhsa_system_sgpr_workgroup_id_x 1
		.amdhsa_system_sgpr_workgroup_id_y 0
		.amdhsa_system_sgpr_workgroup_id_z 0
		.amdhsa_system_sgpr_workgroup_info 0
		.amdhsa_system_vgpr_workitem_id 2
		.amdhsa_next_free_vgpr 256
		.amdhsa_next_free_sgpr 100
		.amdhsa_accum_offset 256
		.amdhsa_reserve_vcc 1
		.amdhsa_float_round_mode_32 0
		.amdhsa_float_round_mode_16_64 0
		.amdhsa_float_denorm_mode_32 3
		.amdhsa_float_denorm_mode_16_64 3
		.amdhsa_dx10_clamp 1
		.amdhsa_ieee_mode 1
		.amdhsa_fp16_overflow 0
		.amdhsa_tg_split 0
		.amdhsa_exception_fp_ieee_invalid_op 0
		.amdhsa_exception_fp_denorm_src 0
		.amdhsa_exception_fp_ieee_div_zero 0
		.amdhsa_exception_fp_ieee_overflow 0
		.amdhsa_exception_fp_ieee_underflow 0
		.amdhsa_exception_fp_ieee_inexact 0
		.amdhsa_exception_int_div_zero 0
	.end_amdhsa_kernel

; __global__ void __launch_bounds__(512, 2) fox_fwd(Args args) {
amdhsa.kernels:
  - .agpr_count:     0
    .args:
      - .offset:         0
        .size:           192
        .value_kind:     by_value
      - .offset:         192
        .size:           4
        .value_kind:     hidden_block_count_x
      - .offset:         196
        .size:           4
        .value_kind:     hidden_block_count_y
      - .offset:         200
        .size:           4
        .value_kind:     hidden_block_count_z
      - .offset:         204
        .size:           2
        .value_kind:     hidden_group_size_x
      - .offset:         206
        .size:           2
        .value_kind:     hidden_group_size_y
      - .offset:         208
        .size:           2
        .value_kind:     hidden_group_size_z
      - .offset:         210
        .size:           2
        .value_kind:     hidden_remainder_x
      - .offset:         212
        .size:           2
        .value_kind:     hidden_remainder_y
      - .offset:         214
        .size:           2
        .value_kind:     hidden_remainder_z
      - .offset:         232
        .size:           8
        .value_kind:     hidden_global_offset_x
      - .offset:         240
        .size:           8
        .value_kind:     hidden_global_offset_y
      - .offset:         248
        .size:           8
        .value_kind:     hidden_global_offset_z
      - .offset:         256
        .size:           2
        .value_kind:     hidden_grid_dims
      - .offset:         280
        .size:           8
        .value_kind:     hidden_multigrid_sync_arg
      - .offset:         312
        .size:           4
        .value_kind:     hidden_dynamic_lds_size
    .group_segment_fixed_size: 0
    .kernarg_segment_align: 8
    .kernarg_segment_size: 448
    .language:       OpenCL C
    .language_version:
      - 2
      - 0
    .max_flat_workgroup_size: 512
    .name:           _Z7fox_fwd4Args
    .private_segment_fixed_size: 0
    .sgpr_count:     106
    .sgpr_spill_count: 16
    .symbol:         _Z7fox_fwd4Args.kd
    .uniform_work_group_size: 1
    .uses_dynamic_stack: false
    .vgpr_count:     256
    .vgpr_spill_count: 0
    .wavefront_size: 64
